# v80 + F and A epilogues: pairs of v_mov_b32 that fill one register pair merged into v_pk_mov_b32 (95 sites)
# baseline (speedup 1.0000x reference)
.LBB0_279:
	s_lshl_b32 s4, s14, 8
	v_or_b32_e32 v122, s36, v153
	s_or_b32 s4, s4, s37
	v_lshrrev_b32_e32 v0, 1, v156
	v_add_u32_e32 v122, s61, v122
	v_mov_b64_e32 v[126:127], s[24:25]
	v_mov_b32_e32 v143, v142
	v_and_or_b32 v0, v0, 24, s4
	v_mad_i64_i32 v[126:127], s[4:5], v122, s49, v[126:127]
	v_cvt_pk_bf16_f32 v157, v128, v129
	v_pk_mov_b32 v[128:129], v[142:143], v[142:143] op_sel:[0,0]
	v_lshl_add_u64 v[126:127], v[0:1], 1, v[126:127]
	v_cvt_pk_bf16_f32 v156, v144, v145
	v_cvt_pk_bf16_f32 v158, v148, v149
	v_cvt_pk_bf16_f32 v159, v146, v147
	v_pk_mul_f32 v[120:121], v[120:121], v[128:129]
	v_pk_mul_f32 v[118:119], v[118:119], v[142:143]
	v_pk_mul_f32 v[116:117], v[116:117], v[128:129]
	s_and_b64 vcc, exec, s[2:3]
	v_pk_mul_f32 v[114:115], v[114:115], v[142:143]
	global_store_dwordx4 v[126:127], v[156:159], off
	s_cbranch_vccnz .LBB0_281
	v_and_b32_e32 v129, 0x7fffffff, v119
	v_and_b32_e32 v128, 0x7fffffff, v118
	v_pk_fma_f32 v[128:129], v[128:129], s[46:47], 1.0 op_sel_hi:[1,0,0]
	v_mov_b64_e32 v[142:143], s[50:51]
	v_rcp_f32_e32 v128, v128
	v_rcp_f32_e32 v129, v129
	v_pk_mul_f32 v[146:147], v[118:119], v[118:119]
	v_cmp_gt_f32_e32 vcc, 0, v118
	v_pk_mul_f32 v[146:147], v[146:147], s[58:59] op_sel_hi:[1,0]
	v_pk_fma_f32 v[144:145], v[128:129], s[48:49], v[142:143] op_sel_hi:[1,0,0]
	v_exp_f32_e32 v146, v146
	v_pk_fma_f32 v[144:145], v[128:129], v[144:145], s[52:53] op_sel_hi:[1,1,0]
	v_exp_f32_e32 v147, v147
	v_pk_fma_f32 v[144:145], v[128:129], v[144:145], s[54:55] op_sel_hi:[1,1,0]
	s_nop 0
	v_pk_fma_f32 v[144:145], v[128:129], v[144:145], s[56:57] op_sel_hi:[1,1,0]
	s_nop 0
	v_pk_mul_f32 v[128:129], v[128:129], v[144:145]
	v_pk_mul_f32 v[144:145], v[120:121], v[120:121]
	v_pk_mul_f32 v[128:129], v[146:147], v[128:129]
	v_pk_mul_f32 v[144:145], v[144:145], s[58:59] op_sel_hi:[1,0]
	v_pk_mul_f32 v[146:147], v[118:119], v[128:129]
	v_pk_fma_f32 v[128:129], v[118:119], v[128:129], v[118:119] neg_lo:[1,0,0] neg_hi:[1,0,0]
	v_exp_f32_e32 v144, v144
	v_cndmask_b32_e32 v118, v128, v146, vcc
	v_cmp_gt_f32_e32 vcc, 0, v119
	v_and_b32_e32 v128, 0x7fffffff, v120
	v_exp_f32_e32 v145, v145
	v_cndmask_b32_e32 v119, v129, v147, vcc
	v_and_b32_e32 v129, 0x7fffffff, v121
	v_pk_fma_f32 v[128:129], v[128:129], s[46:47], 1.0 op_sel_hi:[1,0,0]
	v_cmp_gt_f32_e32 vcc, 0, v120
	v_rcp_f32_e32 v128, v128
	v_rcp_f32_e32 v129, v129
	s_nop 0
	v_pk_fma_f32 v[146:147], v[128:129], s[48:49], v[142:143] op_sel_hi:[1,0,0]
	s_nop 0
	v_pk_fma_f32 v[146:147], v[128:129], v[146:147], s[52:53] op_sel_hi:[1,1,0]
	s_nop 0
	v_pk_fma_f32 v[146:147], v[128:129], v[146:147], s[54:55] op_sel_hi:[1,1,0]
	s_nop 0
	v_pk_fma_f32 v[146:147], v[128:129], v[146:147], s[56:57] op_sel_hi:[1,1,0]
	s_nop 0
	v_pk_mul_f32 v[128:129], v[128:129], v[146:147]
	v_pk_mul_f32 v[146:147], v[114:115], v[114:115]
	v_pk_mul_f32 v[128:129], v[144:145], v[128:129]
	v_pk_mul_f32 v[146:147], v[146:147], s[58:59] op_sel_hi:[1,0]
	v_pk_mul_f32 v[144:145], v[120:121], v[128:129]
	v_pk_fma_f32 v[128:129], v[120:121], v[128:129], v[120:121] neg_lo:[1,0,0] neg_hi:[1,0,0]
	v_exp_f32_e32 v146, v146
	v_cndmask_b32_e32 v120, v128, v144, vcc
	v_cmp_gt_f32_e32 vcc, 0, v121
	v_and_b32_e32 v128, 0x7fffffff, v114
	v_exp_f32_e32 v147, v147
	v_cndmask_b32_e32 v121, v129, v145, vcc
	v_and_b32_e32 v129, 0x7fffffff, v115
	v_pk_fma_f32 v[128:129], v[128:129], s[46:47], 1.0 op_sel_hi:[1,0,0]
	v_cmp_gt_f32_e32 vcc, 0, v114
	v_rcp_f32_e32 v128, v128
	v_rcp_f32_e32 v129, v129
	s_nop 0
	v_pk_fma_f32 v[144:145], v[128:129], s[48:49], v[142:143] op_sel_hi:[1,0,0]
	s_nop 0
	v_pk_fma_f32 v[144:145], v[128:129], v[144:145], s[52:53] op_sel_hi:[1,1,0]
	s_nop 0
	v_pk_fma_f32 v[144:145], v[128:129], v[144:145], s[54:55] op_sel_hi:[1,1,0]
	s_nop 0
	v_pk_fma_f32 v[144:145], v[128:129], v[144:145], s[56:57] op_sel_hi:[1,1,0]
	s_nop 0
	v_pk_mul_f32 v[128:129], v[128:129], v[144:145]
	v_pk_mul_f32 v[144:145], v[116:117], v[116:117]
	v_pk_mul_f32 v[128:129], v[146:147], v[128:129]
	s_nop 0
	v_pk_mul_f32 v[146:147], v[114:115], v[128:129]
	v_pk_fma_f32 v[128:129], v[114:115], v[128:129], v[114:115] neg_lo:[1,0,0] neg_hi:[1,0,0]
	s_nop 0
	v_cndmask_b32_e32 v114, v128, v146, vcc
	v_cmp_gt_f32_e32 vcc, 0, v115
	v_and_b32_e32 v128, 0x7fffffff, v116
	s_nop 0
	v_cndmask_b32_e32 v115, v129, v147, vcc
	v_and_b32_e32 v129, 0x7fffffff, v117
	v_pk_fma_f32 v[128:129], v[128:129], s[46:47], 1.0 op_sel_hi:[1,0,0]
	v_cmp_gt_f32_e32 vcc, 0, v116
	v_rcp_f32_e32 v128, v128
	v_rcp_f32_e32 v129, v129
	s_nop 0
	v_pk_fma_f32 v[142:143], v[128:129], s[48:49], v[142:143] op_sel_hi:[1,0,0]
	s_nop 0
	v_pk_fma_f32 v[142:143], v[128:129], v[142:143], s[52:53] op_sel_hi:[1,1,0]
	s_nop 0
	v_pk_fma_f32 v[142:143], v[128:129], v[142:143], s[54:55] op_sel_hi:[1,1,0]
	s_nop 0
	v_pk_fma_f32 v[142:143], v[128:129], v[142:143], s[56:57] op_sel_hi:[1,1,0]
	s_nop 0
	v_pk_mul_f32 v[128:129], v[128:129], v[142:143]
	v_pk_mul_f32 v[142:143], v[144:145], s[58:59] op_sel_hi:[1,0]
	s_nop 0
	v_exp_f32_e32 v142, v142
	v_exp_f32_e32 v143, v143
	s_nop 0
	v_pk_mul_f32 v[128:129], v[142:143], v[128:129]
	s_nop 0
	v_pk_mul_f32 v[142:143], v[116:117], v[128:129]
	v_pk_fma_f32 v[128:129], v[116:117], v[128:129], v[116:117] neg_lo:[1,0,0] neg_hi:[1,0,0]
	s_nop 0
	v_cndmask_b32_e32 v116, v128, v142, vcc
	v_cmp_gt_f32_e32 vcc, 0, v117
	s_nop 1
	v_cndmask_b32_e32 v117, v129, v143, vcc
.LBB0_281:
	s_and_b64 vcc, exec, s[2:3]
	s_cbranch_vccnz .LBB0_283
	v_pk_mul_f32 v[142:143], v[118:119], v[118:119]
	v_pk_mul_f32 v[128:129], v[120:121], v[120:121]
	v_pk_mov_b32 v[148:149], v[118:119], v[142:143] op_sel:[0,0]
	v_mov_b32_e32 v142, v119
	v_pk_add_f32 v[142:143], v[148:149], v[142:143]
	v_pk_mov_b32 v[148:149], v[120:121], v[128:129] op_sel:[0,0]
	v_mov_b32_e32 v128, v121
	v_pk_mul_f32 v[146:147], v[114:115], v[114:115]
	v_pk_add_f32 v[128:129], v[148:149], v[128:129]
	v_pk_mul_f32 v[144:145], v[116:117], v[116:117]
	v_pk_add_f32 v[128:129], v[142:143], v[128:129]
	v_pk_mov_b32 v[142:143], v[114:115], v[146:147] op_sel:[0,0]
	v_mov_b32_e32 v146, v115
	v_pk_add_f32 v[142:143], v[142:143], v[146:147]
	v_pk_mov_b32 v[146:147], v[116:117], v[144:145] op_sel:[0,0]
	v_mov_b32_e32 v144, v117
	v_pk_add_f32 v[144:145], v[146:147], v[144:145]
	s_nop 0
	v_pk_add_f32 v[142:143], v[142:143], v[144:145]
	s_nop 0
	v_pk_add_f32 v[128:129], v[142:143], v[128:129]
	s_nop 0
	v_pk_add_f32 v[124:125], v[124:125], v[128:129]

.LBB0_291:
	v_pk_mov_b32 v[108:109], v[0:1], v[0:1] op_sel:[1,1]
.LBB0_292:
	v_or_b32_e32 v106, 16, v122
	v_mov_b64_e32 v[110:111], s[24:25]
	v_mov_b32_e32 v115, v114
	v_mad_i64_i32 v[110:111], s[12:13], v106, s49, v[110:111]
	v_cvt_pk_bf16_f32 v127, v112, v113
	v_pk_mov_b32 v[112:113], v[114:115], v[114:115] op_sel:[0,0]
	v_lshl_add_u64 v[110:111], v[0:1], 1, v[110:111]
	v_cvt_pk_bf16_f32 v124, v120, v121
	v_cvt_pk_bf16_f32 v125, v116, v117
	v_cvt_pk_bf16_f32 v126, v118, v119
	v_pk_mul_f32 v[104:105], v[104:105], v[112:113]
	v_pk_mul_f32 v[102:103], v[102:103], v[114:115]
	v_pk_mul_f32 v[100:101], v[100:101], v[112:113]
	s_and_b64 vcc, exec, s[2:3]
	v_pk_mul_f32 v[98:99], v[98:99], v[114:115]
	global_store_dwordx4 v[110:111], v[124:127], off
	s_cbranch_vccnz .LBB0_294
	v_and_b32_e32 v113, 0x7fffffff, v103
	v_and_b32_e32 v112, 0x7fffffff, v102
	v_pk_fma_f32 v[112:113], v[112:113], s[46:47], 1.0 op_sel_hi:[1,0,0]
	v_mov_b64_e32 v[114:115], s[50:51]
	v_rcp_f32_e32 v112, v112
	v_rcp_f32_e32 v113, v113
	v_pk_mul_f32 v[118:119], v[102:103], v[102:103]
	v_cmp_gt_f32_e32 vcc, 0, v102
	v_pk_mul_f32 v[118:119], v[118:119], s[58:59] op_sel_hi:[1,0]
	v_pk_fma_f32 v[116:117], v[112:113], s[48:49], v[114:115] op_sel_hi:[1,0,0]
	v_exp_f32_e32 v118, v118
	v_pk_fma_f32 v[116:117], v[112:113], v[116:117], s[52:53] op_sel_hi:[1,1,0]
	v_exp_f32_e32 v119, v119
	v_pk_fma_f32 v[116:117], v[112:113], v[116:117], s[54:55] op_sel_hi:[1,1,0]
	s_nop 0
	v_pk_fma_f32 v[116:117], v[112:113], v[116:117], s[56:57] op_sel_hi:[1,1,0]
	s_nop 0
	v_pk_mul_f32 v[112:113], v[112:113], v[116:117]
	v_pk_mul_f32 v[116:117], v[104:105], v[104:105]
	v_pk_mul_f32 v[112:113], v[118:119], v[112:113]
	v_pk_mul_f32 v[116:117], v[116:117], s[58:59] op_sel_hi:[1,0]
	v_pk_mul_f32 v[118:119], v[102:103], v[112:113]
	v_pk_fma_f32 v[112:113], v[102:103], v[112:113], v[102:103] neg_lo:[1,0,0] neg_hi:[1,0,0]
	v_exp_f32_e32 v116, v116
	v_cndmask_b32_e32 v102, v112, v118, vcc
	v_cmp_gt_f32_e32 vcc, 0, v103
	v_and_b32_e32 v112, 0x7fffffff, v104
	v_exp_f32_e32 v117, v117
	v_cndmask_b32_e32 v103, v113, v119, vcc
	v_and_b32_e32 v113, 0x7fffffff, v105
	v_pk_fma_f32 v[112:113], v[112:113], s[46:47], 1.0 op_sel_hi:[1,0,0]
	v_cmp_gt_f32_e32 vcc, 0, v104
	v_rcp_f32_e32 v112, v112
	v_rcp_f32_e32 v113, v113
	s_nop 0
	v_pk_fma_f32 v[118:119], v[112:113], s[48:49], v[114:115] op_sel_hi:[1,0,0]
	s_nop 0
	v_pk_fma_f32 v[118:119], v[112:113], v[118:119], s[52:53] op_sel_hi:[1,1,0]
	s_nop 0
	v_pk_fma_f32 v[118:119], v[112:113], v[118:119], s[54:55] op_sel_hi:[1,1,0]
	s_nop 0
	v_pk_fma_f32 v[118:119], v[112:113], v[118:119], s[56:57] op_sel_hi:[1,1,0]
	s_nop 0
	v_pk_mul_f32 v[112:113], v[112:113], v[118:119]
	v_pk_mul_f32 v[118:119], v[98:99], v[98:99]
	v_pk_mul_f32 v[112:113], v[116:117], v[112:113]
	v_pk_mul_f32 v[118:119], v[118:119], s[58:59] op_sel_hi:[1,0]
	v_pk_mul_f32 v[116:117], v[104:105], v[112:113]
	v_pk_fma_f32 v[112:113], v[104:105], v[112:113], v[104:105] neg_lo:[1,0,0] neg_hi:[1,0,0]
	v_exp_f32_e32 v118, v118
	v_cndmask_b32_e32 v104, v112, v116, vcc
	v_cmp_gt_f32_e32 vcc, 0, v105
	v_and_b32_e32 v112, 0x7fffffff, v98
	v_exp_f32_e32 v119, v119
	v_cndmask_b32_e32 v105, v113, v117, vcc
	v_and_b32_e32 v113, 0x7fffffff, v99
	v_pk_fma_f32 v[112:113], v[112:113], s[46:47], 1.0 op_sel_hi:[1,0,0]
	v_cmp_gt_f32_e32 vcc, 0, v98
	v_rcp_f32_e32 v112, v112
	v_rcp_f32_e32 v113, v113
	s_nop 0
	v_pk_fma_f32 v[116:117], v[112:113], s[48:49], v[114:115] op_sel_hi:[1,0,0]
	s_nop 0
	v_pk_fma_f32 v[116:117], v[112:113], v[116:117], s[52:53] op_sel_hi:[1,1,0]
	s_nop 0
	v_pk_fma_f32 v[116:117], v[112:113], v[116:117], s[54:55] op_sel_hi:[1,1,0]
	s_nop 0
	v_pk_fma_f32 v[116:117], v[112:113], v[116:117], s[56:57] op_sel_hi:[1,1,0]
	s_nop 0
	v_pk_mul_f32 v[112:113], v[112:113], v[116:117]
	v_pk_mul_f32 v[116:117], v[100:101], v[100:101]
	v_pk_mul_f32 v[112:113], v[118:119], v[112:113]
	s_nop 0
	v_pk_mul_f32 v[118:119], v[98:99], v[112:113]
	v_pk_fma_f32 v[112:113], v[98:99], v[112:113], v[98:99] neg_lo:[1,0,0] neg_hi:[1,0,0]
	s_nop 0
	v_cndmask_b32_e32 v98, v112, v118, vcc
	v_cmp_gt_f32_e32 vcc, 0, v99
	v_and_b32_e32 v112, 0x7fffffff, v100
	s_nop 0
	v_cndmask_b32_e32 v99, v113, v119, vcc
	v_and_b32_e32 v113, 0x7fffffff, v101
	v_pk_fma_f32 v[112:113], v[112:113], s[46:47], 1.0 op_sel_hi:[1,0,0]
	v_cmp_gt_f32_e32 vcc, 0, v100
	v_rcp_f32_e32 v112, v112
	v_rcp_f32_e32 v113, v113
	s_nop 0
	v_pk_fma_f32 v[114:115], v[112:113], s[48:49], v[114:115] op_sel_hi:[1,0,0]
	s_nop 0
	v_pk_fma_f32 v[114:115], v[112:113], v[114:115], s[52:53] op_sel_hi:[1,1,0]
	s_nop 0
	v_pk_fma_f32 v[114:115], v[112:113], v[114:115], s[54:55] op_sel_hi:[1,1,0]
	s_nop 0
	v_pk_fma_f32 v[114:115], v[112:113], v[114:115], s[56:57] op_sel_hi:[1,1,0]
	s_nop 0
	v_pk_mul_f32 v[112:113], v[112:113], v[114:115]
	v_pk_mul_f32 v[114:115], v[116:117], s[58:59] op_sel_hi:[1,0]
	s_nop 0
	v_exp_f32_e32 v114, v114
	v_exp_f32_e32 v115, v115
	s_nop 0
	v_pk_mul_f32 v[112:113], v[114:115], v[112:113]
	s_nop 0
	v_pk_mul_f32 v[114:115], v[100:101], v[112:113]
	v_pk_fma_f32 v[112:113], v[100:101], v[112:113], v[100:101] neg_lo:[1,0,0] neg_hi:[1,0,0]
	s_nop 0
	v_cndmask_b32_e32 v100, v112, v114, vcc
	v_cmp_gt_f32_e32 vcc, 0, v101
	s_nop 1
	v_cndmask_b32_e32 v101, v113, v115, vcc
.LBB0_294:
	s_and_b64 vcc, exec, s[2:3]
	s_cbranch_vccnz .LBB0_296
	v_pk_mul_f32 v[114:115], v[102:103], v[102:103]
	v_pk_mul_f32 v[112:113], v[104:105], v[104:105]
	v_pk_mov_b32 v[120:121], v[102:103], v[114:115] op_sel:[0,0]
	v_mov_b32_e32 v114, v103
	v_pk_add_f32 v[114:115], v[120:121], v[114:115]
	v_pk_mov_b32 v[120:121], v[104:105], v[112:113] op_sel:[0,0]
	v_mov_b32_e32 v112, v105
	v_pk_mul_f32 v[118:119], v[98:99], v[98:99]
	v_pk_add_f32 v[112:113], v[120:121], v[112:113]
	v_pk_mul_f32 v[116:117], v[100:101], v[100:101]
	v_pk_add_f32 v[112:113], v[114:115], v[112:113]
	v_pk_mov_b32 v[114:115], v[98:99], v[118:119] op_sel:[0,0]
	v_mov_b32_e32 v118, v99
	v_pk_add_f32 v[114:115], v[114:115], v[118:119]
	v_pk_mov_b32 v[118:119], v[100:101], v[116:117] op_sel:[0,0]
	v_mov_b32_e32 v116, v101
	v_pk_add_f32 v[116:117], v[118:119], v[116:117]
	s_nop 0
	v_pk_add_f32 v[114:115], v[114:115], v[116:117]
	s_nop 0
	v_pk_add_f32 v[112:113], v[114:115], v[112:113]
	s_nop 0
	v_pk_add_f32 v[108:109], v[108:109], v[112:113]

.LBB0_304:
	v_pk_mov_b32 v[92:93], v[0:1], v[0:1] op_sel:[1,1]
.LBB0_305:
	v_or_b32_e32 v90, 32, v122
	v_mov_b64_e32 v[94:95], s[24:25]
	v_mov_b32_e32 v99, v98
	v_mad_i64_i32 v[94:95], s[12:13], v90, s49, v[94:95]
	v_cvt_pk_bf16_f32 v107, v96, v97
	v_pk_mov_b32 v[96:97], v[98:99], v[98:99] op_sel:[0,0]
	v_lshl_add_u64 v[94:95], v[0:1], 1, v[94:95]
	v_cvt_pk_bf16_f32 v104, v104, v105
	v_cvt_pk_bf16_f32 v105, v100, v101
	v_cvt_pk_bf16_f32 v106, v102, v103
	v_pk_mul_f32 v[88:89], v[88:89], v[96:97]
	v_pk_mul_f32 v[86:87], v[86:87], v[98:99]
	v_pk_mul_f32 v[84:85], v[84:85], v[96:97]
	s_and_b64 vcc, exec, s[2:3]
	v_pk_mul_f32 v[82:83], v[82:83], v[98:99]
	global_store_dwordx4 v[94:95], v[104:107], off
	s_cbranch_vccnz .LBB0_307
	v_and_b32_e32 v97, 0x7fffffff, v87
	v_and_b32_e32 v96, 0x7fffffff, v86
	v_pk_fma_f32 v[96:97], v[96:97], s[46:47], 1.0 op_sel_hi:[1,0,0]
	v_mov_b64_e32 v[98:99], s[50:51]
	v_rcp_f32_e32 v96, v96
	v_rcp_f32_e32 v97, v97
	v_pk_mul_f32 v[102:103], v[86:87], v[86:87]
	v_cmp_gt_f32_e32 vcc, 0, v86
	v_pk_mul_f32 v[102:103], v[102:103], s[58:59] op_sel_hi:[1,0]
	v_pk_fma_f32 v[100:101], v[96:97], s[48:49], v[98:99] op_sel_hi:[1,0,0]
	v_exp_f32_e32 v102, v102
	v_pk_fma_f32 v[100:101], v[96:97], v[100:101], s[52:53] op_sel_hi:[1,1,0]
	v_exp_f32_e32 v103, v103
	v_pk_fma_f32 v[100:101], v[96:97], v[100:101], s[54:55] op_sel_hi:[1,1,0]
	s_nop 0
	v_pk_fma_f32 v[100:101], v[96:97], v[100:101], s[56:57] op_sel_hi:[1,1,0]
	s_nop 0
	v_pk_mul_f32 v[96:97], v[96:97], v[100:101]
	v_pk_mul_f32 v[100:101], v[88:89], v[88:89]
	v_pk_mul_f32 v[96:97], v[102:103], v[96:97]
	v_pk_mul_f32 v[100:101], v[100:101], s[58:59] op_sel_hi:[1,0]
	v_pk_mul_f32 v[102:103], v[86:87], v[96:97]
	v_pk_fma_f32 v[96:97], v[86:87], v[96:97], v[86:87] neg_lo:[1,0,0] neg_hi:[1,0,0]
	v_exp_f32_e32 v100, v100
	v_cndmask_b32_e32 v86, v96, v102, vcc
	v_cmp_gt_f32_e32 vcc, 0, v87
	v_and_b32_e32 v96, 0x7fffffff, v88
	v_exp_f32_e32 v101, v101
	v_cndmask_b32_e32 v87, v97, v103, vcc
	v_and_b32_e32 v97, 0x7fffffff, v89
	v_pk_fma_f32 v[96:97], v[96:97], s[46:47], 1.0 op_sel_hi:[1,0,0]
	v_cmp_gt_f32_e32 vcc, 0, v88
	v_rcp_f32_e32 v96, v96
	v_rcp_f32_e32 v97, v97
	s_nop 0
	v_pk_fma_f32 v[102:103], v[96:97], s[48:49], v[98:99] op_sel_hi:[1,0,0]
	s_nop 0
	v_pk_fma_f32 v[102:103], v[96:97], v[102:103], s[52:53] op_sel_hi:[1,1,0]
	s_nop 0
	v_pk_fma_f32 v[102:103], v[96:97], v[102:103], s[54:55] op_sel_hi:[1,1,0]
	s_nop 0
	v_pk_fma_f32 v[102:103], v[96:97], v[102:103], s[56:57] op_sel_hi:[1,1,0]
	s_nop 0
	v_pk_mul_f32 v[96:97], v[96:97], v[102:103]
	v_pk_mul_f32 v[102:103], v[82:83], v[82:83]
	v_pk_mul_f32 v[96:97], v[100:101], v[96:97]
	v_pk_mul_f32 v[102:103], v[102:103], s[58:59] op_sel_hi:[1,0]
	v_pk_mul_f32 v[100:101], v[88:89], v[96:97]
	v_pk_fma_f32 v[96:97], v[88:89], v[96:97], v[88:89] neg_lo:[1,0,0] neg_hi:[1,0,0]
	v_exp_f32_e32 v102, v102
	v_cndmask_b32_e32 v88, v96, v100, vcc
	v_cmp_gt_f32_e32 vcc, 0, v89
	v_and_b32_e32 v96, 0x7fffffff, v82
	v_exp_f32_e32 v103, v103
	v_cndmask_b32_e32 v89, v97, v101, vcc
	v_and_b32_e32 v97, 0x7fffffff, v83
	v_pk_fma_f32 v[96:97], v[96:97], s[46:47], 1.0 op_sel_hi:[1,0,0]
	v_cmp_gt_f32_e32 vcc, 0, v82
	v_rcp_f32_e32 v96, v96
	v_rcp_f32_e32 v97, v97
	s_nop 0
	v_pk_fma_f32 v[100:101], v[96:97], s[48:49], v[98:99] op_sel_hi:[1,0,0]
	s_nop 0
	v_pk_fma_f32 v[100:101], v[96:97], v[100:101], s[52:53] op_sel_hi:[1,1,0]
	s_nop 0
	v_pk_fma_f32 v[100:101], v[96:97], v[100:101], s[54:55] op_sel_hi:[1,1,0]
	s_nop 0
	v_pk_fma_f32 v[100:101], v[96:97], v[100:101], s[56:57] op_sel_hi:[1,1,0]
	s_nop 0
	v_pk_mul_f32 v[96:97], v[96:97], v[100:101]
	v_pk_mul_f32 v[100:101], v[84:85], v[84:85]
	v_pk_mul_f32 v[96:97], v[102:103], v[96:97]
	s_nop 0
	v_pk_mul_f32 v[102:103], v[82:83], v[96:97]
	v_pk_fma_f32 v[96:97], v[82:83], v[96:97], v[82:83] neg_lo:[1,0,0] neg_hi:[1,0,0]
	s_nop 0
	v_cndmask_b32_e32 v82, v96, v102, vcc
	v_cmp_gt_f32_e32 vcc, 0, v83
	v_and_b32_e32 v96, 0x7fffffff, v84
	s_nop 0
	v_cndmask_b32_e32 v83, v97, v103, vcc
	v_and_b32_e32 v97, 0x7fffffff, v85
	v_pk_fma_f32 v[96:97], v[96:97], s[46:47], 1.0 op_sel_hi:[1,0,0]
	v_cmp_gt_f32_e32 vcc, 0, v84
	v_rcp_f32_e32 v96, v96
	v_rcp_f32_e32 v97, v97
	s_nop 0
	v_pk_fma_f32 v[98:99], v[96:97], s[48:49], v[98:99] op_sel_hi:[1,0,0]
	s_nop 0
	v_pk_fma_f32 v[98:99], v[96:97], v[98:99], s[52:53] op_sel_hi:[1,1,0]
	s_nop 0
	v_pk_fma_f32 v[98:99], v[96:97], v[98:99], s[54:55] op_sel_hi:[1,1,0]
	s_nop 0
	v_pk_fma_f32 v[98:99], v[96:97], v[98:99], s[56:57] op_sel_hi:[1,1,0]
	s_nop 0
	v_pk_mul_f32 v[96:97], v[96:97], v[98:99]
	v_pk_mul_f32 v[98:99], v[100:101], s[58:59] op_sel_hi:[1,0]
	s_nop 0
	v_exp_f32_e32 v98, v98
	v_exp_f32_e32 v99, v99
	s_nop 0
	v_pk_mul_f32 v[96:97], v[98:99], v[96:97]
	s_nop 0
	v_pk_mul_f32 v[98:99], v[84:85], v[96:97]
	v_pk_fma_f32 v[96:97], v[84:85], v[96:97], v[84:85] neg_lo:[1,0,0] neg_hi:[1,0,0]
	s_nop 0
	v_cndmask_b32_e32 v84, v96, v98, vcc
	v_cmp_gt_f32_e32 vcc, 0, v85
	s_nop 1
	v_cndmask_b32_e32 v85, v97, v99, vcc
.LBB0_307:
	s_and_b64 vcc, exec, s[2:3]
	s_cbranch_vccnz .LBB0_309
	v_pk_mul_f32 v[98:99], v[86:87], v[86:87]
	v_pk_mul_f32 v[96:97], v[88:89], v[88:89]
	v_pk_mov_b32 v[104:105], v[86:87], v[98:99] op_sel:[0,0]
	v_mov_b32_e32 v98, v87
	v_pk_add_f32 v[98:99], v[104:105], v[98:99]
	v_pk_mov_b32 v[104:105], v[88:89], v[96:97] op_sel:[0,0]
	v_mov_b32_e32 v96, v89
	v_pk_mul_f32 v[102:103], v[82:83], v[82:83]
	v_pk_add_f32 v[96:97], v[104:105], v[96:97]
	v_pk_mul_f32 v[100:101], v[84:85], v[84:85]
	v_pk_add_f32 v[96:97], v[98:99], v[96:97]
	v_pk_mov_b32 v[98:99], v[82:83], v[102:103] op_sel:[0,0]
	v_mov_b32_e32 v102, v83
	v_pk_add_f32 v[98:99], v[98:99], v[102:103]
	v_pk_mov_b32 v[102:103], v[84:85], v[100:101] op_sel:[0,0]
	v_mov_b32_e32 v100, v85
	v_pk_add_f32 v[100:101], v[102:103], v[100:101]
	s_nop 0
	v_pk_add_f32 v[98:99], v[98:99], v[100:101]
	s_nop 0
	v_pk_add_f32 v[96:97], v[98:99], v[96:97]
	s_nop 0
	v_pk_add_f32 v[92:93], v[92:93], v[96:97]

.LBB0_317:
	v_pk_mov_b32 v[76:77], v[0:1], v[0:1] op_sel:[1,1]
.LBB0_318:
	v_or_b32_e32 v74, 48, v122
	v_mov_b64_e32 v[78:79], s[24:25]
	v_mov_b32_e32 v83, v82
	v_mad_i64_i32 v[78:79], s[12:13], v74, s49, v[78:79]
	v_cvt_pk_bf16_f32 v91, v80, v81
	v_pk_mov_b32 v[80:81], v[82:83], v[82:83] op_sel:[0,0]
	v_lshl_add_u64 v[78:79], v[0:1], 1, v[78:79]
	v_cvt_pk_bf16_f32 v88, v88, v89
	v_cvt_pk_bf16_f32 v89, v84, v85
	v_cvt_pk_bf16_f32 v90, v86, v87
	v_pk_mul_f32 v[72:73], v[72:73], v[80:81]
	v_pk_mul_f32 v[70:71], v[70:71], v[82:83]
	v_pk_mul_f32 v[68:69], v[68:69], v[80:81]
	s_and_b64 vcc, exec, s[2:3]
	v_pk_mul_f32 v[66:67], v[66:67], v[82:83]
	global_store_dwordx4 v[78:79], v[88:91], off
	s_cbranch_vccnz .LBB0_320
	v_and_b32_e32 v81, 0x7fffffff, v71
	v_and_b32_e32 v80, 0x7fffffff, v70
	v_pk_fma_f32 v[80:81], v[80:81], s[46:47], 1.0 op_sel_hi:[1,0,0]
	v_mov_b64_e32 v[82:83], s[50:51]
	v_rcp_f32_e32 v80, v80
	v_rcp_f32_e32 v81, v81
	v_pk_mul_f32 v[86:87], v[70:71], v[70:71]
	v_cmp_gt_f32_e32 vcc, 0, v70
	v_pk_mul_f32 v[86:87], v[86:87], s[58:59] op_sel_hi:[1,0]
	v_pk_fma_f32 v[84:85], v[80:81], s[48:49], v[82:83] op_sel_hi:[1,0,0]
	v_exp_f32_e32 v86, v86
	v_pk_fma_f32 v[84:85], v[80:81], v[84:85], s[52:53] op_sel_hi:[1,1,0]
	v_exp_f32_e32 v87, v87
	v_pk_fma_f32 v[84:85], v[80:81], v[84:85], s[54:55] op_sel_hi:[1,1,0]
	s_nop 0
	v_pk_fma_f32 v[84:85], v[80:81], v[84:85], s[56:57] op_sel_hi:[1,1,0]
	s_nop 0
	v_pk_mul_f32 v[80:81], v[80:81], v[84:85]
	v_pk_mul_f32 v[84:85], v[72:73], v[72:73]
	v_pk_mul_f32 v[80:81], v[86:87], v[80:81]
	v_pk_mul_f32 v[84:85], v[84:85], s[58:59] op_sel_hi:[1,0]
	v_pk_mul_f32 v[86:87], v[70:71], v[80:81]
	v_pk_fma_f32 v[80:81], v[70:71], v[80:81], v[70:71] neg_lo:[1,0,0] neg_hi:[1,0,0]
	v_exp_f32_e32 v84, v84
	v_cndmask_b32_e32 v70, v80, v86, vcc
	v_cmp_gt_f32_e32 vcc, 0, v71
	v_and_b32_e32 v80, 0x7fffffff, v72
	v_exp_f32_e32 v85, v85
	v_cndmask_b32_e32 v71, v81, v87, vcc
	v_and_b32_e32 v81, 0x7fffffff, v73
	v_pk_fma_f32 v[80:81], v[80:81], s[46:47], 1.0 op_sel_hi:[1,0,0]
	v_cmp_gt_f32_e32 vcc, 0, v72
	v_rcp_f32_e32 v80, v80
	v_rcp_f32_e32 v81, v81
	s_nop 0
	v_pk_fma_f32 v[86:87], v[80:81], s[48:49], v[82:83] op_sel_hi:[1,0,0]
	s_nop 0
	v_pk_fma_f32 v[86:87], v[80:81], v[86:87], s[52:53] op_sel_hi:[1,1,0]
	s_nop 0
	v_pk_fma_f32 v[86:87], v[80:81], v[86:87], s[54:55] op_sel_hi:[1,1,0]
	s_nop 0
	v_pk_fma_f32 v[86:87], v[80:81], v[86:87], s[56:57] op_sel_hi:[1,1,0]
	s_nop 0
	v_pk_mul_f32 v[80:81], v[80:81], v[86:87]
	v_pk_mul_f32 v[86:87], v[66:67], v[66:67]
	v_pk_mul_f32 v[80:81], v[84:85], v[80:81]
	v_pk_mul_f32 v[86:87], v[86:87], s[58:59] op_sel_hi:[1,0]
	v_pk_mul_f32 v[84:85], v[72:73], v[80:81]
	v_pk_fma_f32 v[80:81], v[72:73], v[80:81], v[72:73] neg_lo:[1,0,0] neg_hi:[1,0,0]
	v_exp_f32_e32 v86, v86
	v_cndmask_b32_e32 v72, v80, v84, vcc
	v_cmp_gt_f32_e32 vcc, 0, v73
	v_and_b32_e32 v80, 0x7fffffff, v66
	v_exp_f32_e32 v87, v87
	v_cndmask_b32_e32 v73, v81, v85, vcc
	v_and_b32_e32 v81, 0x7fffffff, v67
	v_pk_fma_f32 v[80:81], v[80:81], s[46:47], 1.0 op_sel_hi:[1,0,0]
	v_cmp_gt_f32_e32 vcc, 0, v66
	v_rcp_f32_e32 v80, v80
	v_rcp_f32_e32 v81, v81
	s_nop 0
	v_pk_fma_f32 v[84:85], v[80:81], s[48:49], v[82:83] op_sel_hi:[1,0,0]
	s_nop 0
	v_pk_fma_f32 v[84:85], v[80:81], v[84:85], s[52:53] op_sel_hi:[1,1,0]
	s_nop 0
	v_pk_fma_f32 v[84:85], v[80:81], v[84:85], s[54:55] op_sel_hi:[1,1,0]
	s_nop 0
	v_pk_fma_f32 v[84:85], v[80:81], v[84:85], s[56:57] op_sel_hi:[1,1,0]
	s_nop 0
	v_pk_mul_f32 v[80:81], v[80:81], v[84:85]
	v_pk_mul_f32 v[84:85], v[68:69], v[68:69]
	v_pk_mul_f32 v[80:81], v[86:87], v[80:81]
	s_nop 0
	v_pk_mul_f32 v[86:87], v[66:67], v[80:81]
	v_pk_fma_f32 v[80:81], v[66:67], v[80:81], v[66:67] neg_lo:[1,0,0] neg_hi:[1,0,0]
	s_nop 0
	v_cndmask_b32_e32 v66, v80, v86, vcc
	v_cmp_gt_f32_e32 vcc, 0, v67
	v_and_b32_e32 v80, 0x7fffffff, v68
	s_nop 0
	v_cndmask_b32_e32 v67, v81, v87, vcc
	v_and_b32_e32 v81, 0x7fffffff, v69
	v_pk_fma_f32 v[80:81], v[80:81], s[46:47], 1.0 op_sel_hi:[1,0,0]
	v_cmp_gt_f32_e32 vcc, 0, v68
	v_rcp_f32_e32 v80, v80
	v_rcp_f32_e32 v81, v81
	s_nop 0
	v_pk_fma_f32 v[82:83], v[80:81], s[48:49], v[82:83] op_sel_hi:[1,0,0]
	s_nop 0
	v_pk_fma_f32 v[82:83], v[80:81], v[82:83], s[52:53] op_sel_hi:[1,1,0]
	s_nop 0
	v_pk_fma_f32 v[82:83], v[80:81], v[82:83], s[54:55] op_sel_hi:[1,1,0]
	s_nop 0
	v_pk_fma_f32 v[82:83], v[80:81], v[82:83], s[56:57] op_sel_hi:[1,1,0]
	s_nop 0
	v_pk_mul_f32 v[80:81], v[80:81], v[82:83]
	v_pk_mul_f32 v[82:83], v[84:85], s[58:59] op_sel_hi:[1,0]
	s_nop 0
	v_exp_f32_e32 v82, v82
	v_exp_f32_e32 v83, v83
	s_nop 0
	v_pk_mul_f32 v[80:81], v[82:83], v[80:81]
	s_nop 0
	v_pk_mul_f32 v[82:83], v[68:69], v[80:81]
	v_pk_fma_f32 v[80:81], v[68:69], v[80:81], v[68:69] neg_lo:[1,0,0] neg_hi:[1,0,0]
	s_nop 0
	v_cndmask_b32_e32 v68, v80, v82, vcc
	v_cmp_gt_f32_e32 vcc, 0, v69
	s_nop 1
	v_cndmask_b32_e32 v69, v81, v83, vcc
.LBB0_320:
	s_and_b64 vcc, exec, s[2:3]
	s_cbranch_vccnz .LBB0_322
	v_pk_mul_f32 v[82:83], v[70:71], v[70:71]
	v_pk_mul_f32 v[80:81], v[72:73], v[72:73]
	v_pk_mov_b32 v[88:89], v[70:71], v[82:83] op_sel:[0,0]
	v_mov_b32_e32 v82, v71
	v_pk_add_f32 v[82:83], v[88:89], v[82:83]
	v_pk_mov_b32 v[88:89], v[72:73], v[80:81] op_sel:[0,0]
	v_mov_b32_e32 v80, v73
	v_pk_mul_f32 v[86:87], v[66:67], v[66:67]
	v_pk_add_f32 v[80:81], v[88:89], v[80:81]
	v_pk_mul_f32 v[84:85], v[68:69], v[68:69]
	v_pk_add_f32 v[80:81], v[82:83], v[80:81]
	v_pk_mov_b32 v[82:83], v[66:67], v[86:87] op_sel:[0,0]
	v_mov_b32_e32 v86, v67
	v_pk_add_f32 v[82:83], v[82:83], v[86:87]
	v_pk_mov_b32 v[86:87], v[68:69], v[84:85] op_sel:[0,0]
	v_mov_b32_e32 v84, v69
	v_pk_add_f32 v[84:85], v[86:87], v[84:85]
	s_nop 0
	v_pk_add_f32 v[82:83], v[82:83], v[84:85]
	s_nop 0
	v_pk_add_f32 v[80:81], v[82:83], v[80:81]
	s_nop 0
	v_pk_add_f32 v[76:77], v[76:77], v[80:81]

.LBB0_330:
	v_pk_mov_b32 v[60:61], v[0:1], v[0:1] op_sel:[1,1]
.LBB0_331:
	v_add_u32_e32 v58, 0x80, v122
	v_mov_b64_e32 v[62:63], s[24:25]
	v_mov_b32_e32 v67, v66
	v_mad_i64_i32 v[62:63], s[12:13], v58, s49, v[62:63]
	v_cvt_pk_bf16_f32 v75, v64, v65
	v_pk_mov_b32 v[64:65], v[66:67], v[66:67] op_sel:[0,0]
	v_lshl_add_u64 v[62:63], v[0:1], 1, v[62:63]
	v_cvt_pk_bf16_f32 v72, v72, v73
	v_cvt_pk_bf16_f32 v73, v68, v69
	v_cvt_pk_bf16_f32 v74, v70, v71
	v_pk_mul_f32 v[56:57], v[56:57], v[64:65]
	v_pk_mul_f32 v[54:55], v[54:55], v[66:67]
	v_pk_mul_f32 v[52:53], v[52:53], v[64:65]
	s_and_b64 vcc, exec, s[2:3]
	v_pk_mul_f32 v[50:51], v[50:51], v[66:67]
	global_store_dwordx4 v[62:63], v[72:75], off
	s_cbranch_vccnz .LBB0_333
	v_and_b32_e32 v65, 0x7fffffff, v55
	v_and_b32_e32 v64, 0x7fffffff, v54
	v_pk_fma_f32 v[64:65], v[64:65], s[46:47], 1.0 op_sel_hi:[1,0,0]
	v_mov_b64_e32 v[66:67], s[50:51]
	v_rcp_f32_e32 v64, v64
	v_rcp_f32_e32 v65, v65
	v_pk_mul_f32 v[70:71], v[54:55], v[54:55]
	v_cmp_gt_f32_e32 vcc, 0, v54
	v_pk_mul_f32 v[70:71], v[70:71], s[58:59] op_sel_hi:[1,0]
	v_pk_fma_f32 v[68:69], v[64:65], s[48:49], v[66:67] op_sel_hi:[1,0,0]
	v_exp_f32_e32 v70, v70
	v_pk_fma_f32 v[68:69], v[64:65], v[68:69], s[52:53] op_sel_hi:[1,1,0]
	v_exp_f32_e32 v71, v71
	v_pk_fma_f32 v[68:69], v[64:65], v[68:69], s[54:55] op_sel_hi:[1,1,0]
	s_nop 0
	v_pk_fma_f32 v[68:69], v[64:65], v[68:69], s[56:57] op_sel_hi:[1,1,0]
	s_nop 0
	v_pk_mul_f32 v[64:65], v[64:65], v[68:69]
	v_pk_mul_f32 v[68:69], v[56:57], v[56:57]
	v_pk_mul_f32 v[64:65], v[70:71], v[64:65]
	v_pk_mul_f32 v[68:69], v[68:69], s[58:59] op_sel_hi:[1,0]
	v_pk_mul_f32 v[70:71], v[54:55], v[64:65]
	v_pk_fma_f32 v[64:65], v[54:55], v[64:65], v[54:55] neg_lo:[1,0,0] neg_hi:[1,0,0]
	v_exp_f32_e32 v68, v68
	v_cndmask_b32_e32 v54, v64, v70, vcc
	v_cmp_gt_f32_e32 vcc, 0, v55
	v_and_b32_e32 v64, 0x7fffffff, v56
	v_exp_f32_e32 v69, v69
	v_cndmask_b32_e32 v55, v65, v71, vcc
	v_and_b32_e32 v65, 0x7fffffff, v57
	v_pk_fma_f32 v[64:65], v[64:65], s[46:47], 1.0 op_sel_hi:[1,0,0]
	v_cmp_gt_f32_e32 vcc, 0, v56
	v_rcp_f32_e32 v64, v64
	v_rcp_f32_e32 v65, v65
	s_nop 0
	v_pk_fma_f32 v[70:71], v[64:65], s[48:49], v[66:67] op_sel_hi:[1,0,0]
	s_nop 0
	v_pk_fma_f32 v[70:71], v[64:65], v[70:71], s[52:53] op_sel_hi:[1,1,0]
	s_nop 0
	v_pk_fma_f32 v[70:71], v[64:65], v[70:71], s[54:55] op_sel_hi:[1,1,0]
	s_nop 0
	v_pk_fma_f32 v[70:71], v[64:65], v[70:71], s[56:57] op_sel_hi:[1,1,0]
	s_nop 0
	v_pk_mul_f32 v[64:65], v[64:65], v[70:71]
	v_pk_mul_f32 v[70:71], v[50:51], v[50:51]
	v_pk_mul_f32 v[64:65], v[68:69], v[64:65]
	v_pk_mul_f32 v[70:71], v[70:71], s[58:59] op_sel_hi:[1,0]
	v_pk_mul_f32 v[68:69], v[56:57], v[64:65]
	v_pk_fma_f32 v[64:65], v[56:57], v[64:65], v[56:57] neg_lo:[1,0,0] neg_hi:[1,0,0]
	v_exp_f32_e32 v70, v70
	v_cndmask_b32_e32 v56, v64, v68, vcc
	v_cmp_gt_f32_e32 vcc, 0, v57
	v_and_b32_e32 v64, 0x7fffffff, v50
	v_exp_f32_e32 v71, v71
	v_cndmask_b32_e32 v57, v65, v69, vcc
	v_and_b32_e32 v65, 0x7fffffff, v51
	v_pk_fma_f32 v[64:65], v[64:65], s[46:47], 1.0 op_sel_hi:[1,0,0]
	v_cmp_gt_f32_e32 vcc, 0, v50
	v_rcp_f32_e32 v64, v64
	v_rcp_f32_e32 v65, v65
	s_nop 0
	v_pk_fma_f32 v[68:69], v[64:65], s[48:49], v[66:67] op_sel_hi:[1,0,0]
	s_nop 0
	v_pk_fma_f32 v[68:69], v[64:65], v[68:69], s[52:53] op_sel_hi:[1,1,0]
	s_nop 0
	v_pk_fma_f32 v[68:69], v[64:65], v[68:69], s[54:55] op_sel_hi:[1,1,0]
	s_nop 0
	v_pk_fma_f32 v[68:69], v[64:65], v[68:69], s[56:57] op_sel_hi:[1,1,0]
	s_nop 0
	v_pk_mul_f32 v[64:65], v[64:65], v[68:69]
	v_pk_mul_f32 v[68:69], v[52:53], v[52:53]
	v_pk_mul_f32 v[64:65], v[70:71], v[64:65]
	s_nop 0
	v_pk_mul_f32 v[70:71], v[50:51], v[64:65]
	v_pk_fma_f32 v[64:65], v[50:51], v[64:65], v[50:51] neg_lo:[1,0,0] neg_hi:[1,0,0]
	s_nop 0
	v_cndmask_b32_e32 v50, v64, v70, vcc
	v_cmp_gt_f32_e32 vcc, 0, v51
	v_and_b32_e32 v64, 0x7fffffff, v52
	s_nop 0
	v_cndmask_b32_e32 v51, v65, v71, vcc
	v_and_b32_e32 v65, 0x7fffffff, v53
	v_pk_fma_f32 v[64:65], v[64:65], s[46:47], 1.0 op_sel_hi:[1,0,0]
	v_cmp_gt_f32_e32 vcc, 0, v52
	v_rcp_f32_e32 v64, v64
	v_rcp_f32_e32 v65, v65
	s_nop 0
	v_pk_fma_f32 v[66:67], v[64:65], s[48:49], v[66:67] op_sel_hi:[1,0,0]
	s_nop 0
	v_pk_fma_f32 v[66:67], v[64:65], v[66:67], s[52:53] op_sel_hi:[1,1,0]
	s_nop 0
	v_pk_fma_f32 v[66:67], v[64:65], v[66:67], s[54:55] op_sel_hi:[1,1,0]
	s_nop 0
	v_pk_fma_f32 v[66:67], v[64:65], v[66:67], s[56:57] op_sel_hi:[1,1,0]
	s_nop 0
	v_pk_mul_f32 v[64:65], v[64:65], v[66:67]
	v_pk_mul_f32 v[66:67], v[68:69], s[58:59] op_sel_hi:[1,0]
	s_nop 0
	v_exp_f32_e32 v66, v66
	v_exp_f32_e32 v67, v67
	s_nop 0
	v_pk_mul_f32 v[64:65], v[66:67], v[64:65]
	s_nop 0
	v_pk_mul_f32 v[66:67], v[52:53], v[64:65]
	v_pk_fma_f32 v[64:65], v[52:53], v[64:65], v[52:53] neg_lo:[1,0,0] neg_hi:[1,0,0]
	s_nop 0
	v_cndmask_b32_e32 v52, v64, v66, vcc
	v_cmp_gt_f32_e32 vcc, 0, v53
	s_nop 1
	v_cndmask_b32_e32 v53, v65, v67, vcc
.LBB0_333:
	s_and_b64 vcc, exec, s[2:3]
	s_cbranch_vccnz .LBB0_335
	v_pk_mul_f32 v[66:67], v[54:55], v[54:55]
	v_pk_mul_f32 v[64:65], v[56:57], v[56:57]
	v_pk_mov_b32 v[72:73], v[54:55], v[66:67] op_sel:[0,0]
	v_mov_b32_e32 v66, v55
	v_pk_add_f32 v[66:67], v[72:73], v[66:67]
	v_pk_mov_b32 v[72:73], v[56:57], v[64:65] op_sel:[0,0]
	v_mov_b32_e32 v64, v57
	v_pk_mul_f32 v[70:71], v[50:51], v[50:51]
	v_pk_add_f32 v[64:65], v[72:73], v[64:65]
	v_pk_mul_f32 v[68:69], v[52:53], v[52:53]
	v_pk_add_f32 v[64:65], v[66:67], v[64:65]
	v_pk_mov_b32 v[66:67], v[50:51], v[70:71] op_sel:[0,0]
	v_mov_b32_e32 v70, v51
	v_pk_add_f32 v[66:67], v[66:67], v[70:71]
	v_pk_mov_b32 v[70:71], v[52:53], v[68:69] op_sel:[0,0]
	v_mov_b32_e32 v68, v53
	v_pk_add_f32 v[68:69], v[70:71], v[68:69]
	s_nop 0
	v_pk_add_f32 v[66:67], v[66:67], v[68:69]
	s_nop 0
	v_pk_add_f32 v[64:65], v[66:67], v[64:65]
	s_nop 0
	v_pk_add_f32 v[60:61], v[60:61], v[64:65]

.LBB0_343:
	v_pk_mov_b32 v[44:45], v[0:1], v[0:1] op_sel:[1,1]
.LBB0_344:
	v_add_u32_e32 v42, 0x90, v122
	v_mov_b64_e32 v[46:47], s[24:25]
	v_mov_b32_e32 v51, v50
	v_mad_i64_i32 v[46:47], s[12:13], v42, s49, v[46:47]
	v_cvt_pk_bf16_f32 v59, v48, v49
	v_pk_mov_b32 v[48:49], v[50:51], v[50:51] op_sel:[0,0]
	v_lshl_add_u64 v[46:47], v[0:1], 1, v[46:47]
	v_cvt_pk_bf16_f32 v56, v56, v57
	v_cvt_pk_bf16_f32 v57, v52, v53
	v_cvt_pk_bf16_f32 v58, v54, v55
	v_pk_mul_f32 v[40:41], v[40:41], v[48:49]
	v_pk_mul_f32 v[38:39], v[38:39], v[50:51]
	v_pk_mul_f32 v[36:37], v[36:37], v[48:49]
	s_and_b64 vcc, exec, s[2:3]
	v_pk_mul_f32 v[34:35], v[34:35], v[50:51]
	global_store_dwordx4 v[46:47], v[56:59], off
	s_cbranch_vccnz .LBB0_346
	v_and_b32_e32 v49, 0x7fffffff, v39
	v_and_b32_e32 v48, 0x7fffffff, v38
	v_pk_fma_f32 v[48:49], v[48:49], s[46:47], 1.0 op_sel_hi:[1,0,0]
	v_mov_b64_e32 v[50:51], s[50:51]
	v_rcp_f32_e32 v48, v48
	v_rcp_f32_e32 v49, v49
	v_pk_mul_f32 v[54:55], v[38:39], v[38:39]
	v_cmp_gt_f32_e32 vcc, 0, v38
	v_pk_mul_f32 v[54:55], v[54:55], s[58:59] op_sel_hi:[1,0]
	v_pk_fma_f32 v[52:53], v[48:49], s[48:49], v[50:51] op_sel_hi:[1,0,0]
	v_exp_f32_e32 v54, v54
	v_pk_fma_f32 v[52:53], v[48:49], v[52:53], s[52:53] op_sel_hi:[1,1,0]
	v_exp_f32_e32 v55, v55
	v_pk_fma_f32 v[52:53], v[48:49], v[52:53], s[54:55] op_sel_hi:[1,1,0]
	s_nop 0
	v_pk_fma_f32 v[52:53], v[48:49], v[52:53], s[56:57] op_sel_hi:[1,1,0]
	s_nop 0
	v_pk_mul_f32 v[48:49], v[48:49], v[52:53]
	v_pk_mul_f32 v[52:53], v[40:41], v[40:41]
	v_pk_mul_f32 v[48:49], v[54:55], v[48:49]
	v_pk_mul_f32 v[52:53], v[52:53], s[58:59] op_sel_hi:[1,0]
	v_pk_mul_f32 v[54:55], v[38:39], v[48:49]
	v_pk_fma_f32 v[48:49], v[38:39], v[48:49], v[38:39] neg_lo:[1,0,0] neg_hi:[1,0,0]
	v_exp_f32_e32 v52, v52
	v_cndmask_b32_e32 v38, v48, v54, vcc
	v_cmp_gt_f32_e32 vcc, 0, v39
	v_and_b32_e32 v48, 0x7fffffff, v40
	v_exp_f32_e32 v53, v53
	v_cndmask_b32_e32 v39, v49, v55, vcc
	v_and_b32_e32 v49, 0x7fffffff, v41
	v_pk_fma_f32 v[48:49], v[48:49], s[46:47], 1.0 op_sel_hi:[1,0,0]
	v_cmp_gt_f32_e32 vcc, 0, v40
	v_rcp_f32_e32 v48, v48
	v_rcp_f32_e32 v49, v49
	s_nop 0
	v_pk_fma_f32 v[54:55], v[48:49], s[48:49], v[50:51] op_sel_hi:[1,0,0]
	s_nop 0
	v_pk_fma_f32 v[54:55], v[48:49], v[54:55], s[52:53] op_sel_hi:[1,1,0]
	s_nop 0
	v_pk_fma_f32 v[54:55], v[48:49], v[54:55], s[54:55] op_sel_hi:[1,1,0]
	s_nop 0
	v_pk_fma_f32 v[54:55], v[48:49], v[54:55], s[56:57] op_sel_hi:[1,1,0]
	s_nop 0
	v_pk_mul_f32 v[48:49], v[48:49], v[54:55]
	v_pk_mul_f32 v[54:55], v[34:35], v[34:35]
	v_pk_mul_f32 v[48:49], v[52:53], v[48:49]
	v_pk_mul_f32 v[54:55], v[54:55], s[58:59] op_sel_hi:[1,0]
	v_pk_mul_f32 v[52:53], v[40:41], v[48:49]
	v_pk_fma_f32 v[48:49], v[40:41], v[48:49], v[40:41] neg_lo:[1,0,0] neg_hi:[1,0,0]
	v_exp_f32_e32 v54, v54
	v_cndmask_b32_e32 v40, v48, v52, vcc
	v_cmp_gt_f32_e32 vcc, 0, v41
	v_and_b32_e32 v48, 0x7fffffff, v34
	v_exp_f32_e32 v55, v55
	v_cndmask_b32_e32 v41, v49, v53, vcc
	v_and_b32_e32 v49, 0x7fffffff, v35
	v_pk_fma_f32 v[48:49], v[48:49], s[46:47], 1.0 op_sel_hi:[1,0,0]
	v_cmp_gt_f32_e32 vcc, 0, v34
	v_rcp_f32_e32 v48, v48
	v_rcp_f32_e32 v49, v49
	s_nop 0
	v_pk_fma_f32 v[52:53], v[48:49], s[48:49], v[50:51] op_sel_hi:[1,0,0]
	s_nop 0
	v_pk_fma_f32 v[52:53], v[48:49], v[52:53], s[52:53] op_sel_hi:[1,1,0]
	s_nop 0
	v_pk_fma_f32 v[52:53], v[48:49], v[52:53], s[54:55] op_sel_hi:[1,1,0]
	s_nop 0
	v_pk_fma_f32 v[52:53], v[48:49], v[52:53], s[56:57] op_sel_hi:[1,1,0]
	s_nop 0
	v_pk_mul_f32 v[48:49], v[48:49], v[52:53]
	v_pk_mul_f32 v[52:53], v[36:37], v[36:37]
	v_pk_mul_f32 v[48:49], v[54:55], v[48:49]
	s_nop 0
	v_pk_mul_f32 v[54:55], v[34:35], v[48:49]
	v_pk_fma_f32 v[48:49], v[34:35], v[48:49], v[34:35] neg_lo:[1,0,0] neg_hi:[1,0,0]
	s_nop 0
	v_cndmask_b32_e32 v34, v48, v54, vcc
	v_cmp_gt_f32_e32 vcc, 0, v35
	v_and_b32_e32 v48, 0x7fffffff, v36
	s_nop 0
	v_cndmask_b32_e32 v35, v49, v55, vcc
	v_and_b32_e32 v49, 0x7fffffff, v37
	v_pk_fma_f32 v[48:49], v[48:49], s[46:47], 1.0 op_sel_hi:[1,0,0]
	v_cmp_gt_f32_e32 vcc, 0, v36
	v_rcp_f32_e32 v48, v48
	v_rcp_f32_e32 v49, v49
	s_nop 0
	v_pk_fma_f32 v[50:51], v[48:49], s[48:49], v[50:51] op_sel_hi:[1,0,0]
	s_nop 0
	v_pk_fma_f32 v[50:51], v[48:49], v[50:51], s[52:53] op_sel_hi:[1,1,0]
	s_nop 0
	v_pk_fma_f32 v[50:51], v[48:49], v[50:51], s[54:55] op_sel_hi:[1,1,0]
	s_nop 0
	v_pk_fma_f32 v[50:51], v[48:49], v[50:51], s[56:57] op_sel_hi:[1,1,0]
	s_nop 0
	v_pk_mul_f32 v[48:49], v[48:49], v[50:51]
	v_pk_mul_f32 v[50:51], v[52:53], s[58:59] op_sel_hi:[1,0]
	s_nop 0
	v_exp_f32_e32 v50, v50
	v_exp_f32_e32 v51, v51
	s_nop 0
	v_pk_mul_f32 v[48:49], v[50:51], v[48:49]
	s_nop 0
	v_pk_mul_f32 v[50:51], v[36:37], v[48:49]
	v_pk_fma_f32 v[48:49], v[36:37], v[48:49], v[36:37] neg_lo:[1,0,0] neg_hi:[1,0,0]
	s_nop 0
	v_cndmask_b32_e32 v36, v48, v50, vcc
	v_cmp_gt_f32_e32 vcc, 0, v37
	s_nop 1
	v_cndmask_b32_e32 v37, v49, v51, vcc
.LBB0_346:
	s_and_b64 vcc, exec, s[2:3]
	s_cbranch_vccnz .LBB0_348
	v_pk_mul_f32 v[50:51], v[38:39], v[38:39]
	v_pk_mul_f32 v[48:49], v[40:41], v[40:41]
	v_pk_mov_b32 v[56:57], v[38:39], v[50:51] op_sel:[0,0]
	v_mov_b32_e32 v50, v39
	v_pk_add_f32 v[50:51], v[56:57], v[50:51]
	v_pk_mov_b32 v[56:57], v[40:41], v[48:49] op_sel:[0,0]
	v_mov_b32_e32 v48, v41
	v_pk_mul_f32 v[54:55], v[34:35], v[34:35]
	v_pk_add_f32 v[48:49], v[56:57], v[48:49]
	v_pk_mul_f32 v[52:53], v[36:37], v[36:37]
	v_pk_add_f32 v[48:49], v[50:51], v[48:49]
	v_pk_mov_b32 v[50:51], v[34:35], v[54:55] op_sel:[0,0]
	v_mov_b32_e32 v54, v35
	v_pk_add_f32 v[50:51], v[50:51], v[54:55]
	v_pk_mov_b32 v[54:55], v[36:37], v[52:53] op_sel:[0,0]
	v_mov_b32_e32 v52, v37
	v_pk_add_f32 v[52:53], v[54:55], v[52:53]
	s_nop 0
	v_pk_add_f32 v[50:51], v[50:51], v[52:53]
	s_nop 0
	v_pk_add_f32 v[48:49], v[50:51], v[48:49]
	s_nop 0
	v_pk_add_f32 v[44:45], v[44:45], v[48:49]

.LBB0_356:
	v_pk_mov_b32 v[28:29], v[0:1], v[0:1] op_sel:[1,1]
.LBB0_357:
	v_add_u32_e32 v26, 0xa0, v122
	v_mov_b64_e32 v[30:31], s[24:25]
	v_mov_b32_e32 v35, v34
	v_mad_i64_i32 v[30:31], s[12:13], v26, s49, v[30:31]
	v_cvt_pk_bf16_f32 v43, v32, v33
	v_pk_mov_b32 v[32:33], v[34:35], v[34:35] op_sel:[0,0]
	v_lshl_add_u64 v[30:31], v[0:1], 1, v[30:31]
	v_cvt_pk_bf16_f32 v40, v40, v41
	v_cvt_pk_bf16_f32 v41, v36, v37
	v_cvt_pk_bf16_f32 v42, v38, v39
	v_pk_mul_f32 v[24:25], v[24:25], v[32:33]
	v_pk_mul_f32 v[22:23], v[22:23], v[34:35]
	v_pk_mul_f32 v[20:21], v[20:21], v[32:33]
	s_and_b64 vcc, exec, s[2:3]
	v_pk_mul_f32 v[18:19], v[18:19], v[34:35]
	global_store_dwordx4 v[30:31], v[40:43], off
	s_cbranch_vccnz .LBB0_359
	v_and_b32_e32 v33, 0x7fffffff, v23
	v_and_b32_e32 v32, 0x7fffffff, v22
	v_pk_fma_f32 v[32:33], v[32:33], s[46:47], 1.0 op_sel_hi:[1,0,0]
	v_mov_b64_e32 v[34:35], s[50:51]
	v_rcp_f32_e32 v32, v32
	v_rcp_f32_e32 v33, v33
	v_pk_mul_f32 v[38:39], v[22:23], v[22:23]
	v_cmp_gt_f32_e32 vcc, 0, v22
	v_pk_mul_f32 v[38:39], v[38:39], s[58:59] op_sel_hi:[1,0]
	v_pk_fma_f32 v[36:37], v[32:33], s[48:49], v[34:35] op_sel_hi:[1,0,0]
	v_exp_f32_e32 v38, v38
	v_pk_fma_f32 v[36:37], v[32:33], v[36:37], s[52:53] op_sel_hi:[1,1,0]
	v_exp_f32_e32 v39, v39
	v_pk_fma_f32 v[36:37], v[32:33], v[36:37], s[54:55] op_sel_hi:[1,1,0]
	s_nop 0
	v_pk_fma_f32 v[36:37], v[32:33], v[36:37], s[56:57] op_sel_hi:[1,1,0]
	s_nop 0
	v_pk_mul_f32 v[32:33], v[32:33], v[36:37]
	v_pk_mul_f32 v[36:37], v[24:25], v[24:25]
	v_pk_mul_f32 v[32:33], v[38:39], v[32:33]
	v_pk_mul_f32 v[36:37], v[36:37], s[58:59] op_sel_hi:[1,0]
	v_pk_mul_f32 v[38:39], v[22:23], v[32:33]
	v_pk_fma_f32 v[32:33], v[22:23], v[32:33], v[22:23] neg_lo:[1,0,0] neg_hi:[1,0,0]
	v_exp_f32_e32 v36, v36
	v_cndmask_b32_e32 v22, v32, v38, vcc
	v_cmp_gt_f32_e32 vcc, 0, v23
	v_and_b32_e32 v32, 0x7fffffff, v24
	v_exp_f32_e32 v37, v37
	v_cndmask_b32_e32 v23, v33, v39, vcc
	v_and_b32_e32 v33, 0x7fffffff, v25
	v_pk_fma_f32 v[32:33], v[32:33], s[46:47], 1.0 op_sel_hi:[1,0,0]
	v_cmp_gt_f32_e32 vcc, 0, v24
	v_rcp_f32_e32 v32, v32
	v_rcp_f32_e32 v33, v33
	s_nop 0
	v_pk_fma_f32 v[38:39], v[32:33], s[48:49], v[34:35] op_sel_hi:[1,0,0]
	s_nop 0
	v_pk_fma_f32 v[38:39], v[32:33], v[38:39], s[52:53] op_sel_hi:[1,1,0]
	s_nop 0
	v_pk_fma_f32 v[38:39], v[32:33], v[38:39], s[54:55] op_sel_hi:[1,1,0]
	s_nop 0
	v_pk_fma_f32 v[38:39], v[32:33], v[38:39], s[56:57] op_sel_hi:[1,1,0]
	s_nop 0
	v_pk_mul_f32 v[32:33], v[32:33], v[38:39]
	v_pk_mul_f32 v[38:39], v[18:19], v[18:19]
	v_pk_mul_f32 v[32:33], v[36:37], v[32:33]
	v_pk_mul_f32 v[38:39], v[38:39], s[58:59] op_sel_hi:[1,0]
	v_pk_mul_f32 v[36:37], v[24:25], v[32:33]
	v_pk_fma_f32 v[32:33], v[24:25], v[32:33], v[24:25] neg_lo:[1,0,0] neg_hi:[1,0,0]
	v_exp_f32_e32 v38, v38
	v_cndmask_b32_e32 v24, v32, v36, vcc
	v_cmp_gt_f32_e32 vcc, 0, v25
	v_and_b32_e32 v32, 0x7fffffff, v18
	v_exp_f32_e32 v39, v39
	v_cndmask_b32_e32 v25, v33, v37, vcc
	v_and_b32_e32 v33, 0x7fffffff, v19
	v_pk_fma_f32 v[32:33], v[32:33], s[46:47], 1.0 op_sel_hi:[1,0,0]
	v_cmp_gt_f32_e32 vcc, 0, v18
	v_rcp_f32_e32 v32, v32
	v_rcp_f32_e32 v33, v33
	s_nop 0
	v_pk_fma_f32 v[36:37], v[32:33], s[48:49], v[34:35] op_sel_hi:[1,0,0]
	s_nop 0
	v_pk_fma_f32 v[36:37], v[32:33], v[36:37], s[52:53] op_sel_hi:[1,1,0]
	s_nop 0
	v_pk_fma_f32 v[36:37], v[32:33], v[36:37], s[54:55] op_sel_hi:[1,1,0]
	s_nop 0
	v_pk_fma_f32 v[36:37], v[32:33], v[36:37], s[56:57] op_sel_hi:[1,1,0]
	s_nop 0
	v_pk_mul_f32 v[32:33], v[32:33], v[36:37]
	v_pk_mul_f32 v[36:37], v[20:21], v[20:21]
	v_pk_mul_f32 v[32:33], v[38:39], v[32:33]
	s_nop 0
	v_pk_mul_f32 v[38:39], v[18:19], v[32:33]
	v_pk_fma_f32 v[32:33], v[18:19], v[32:33], v[18:19] neg_lo:[1,0,0] neg_hi:[1,0,0]
	s_nop 0
	v_cndmask_b32_e32 v18, v32, v38, vcc
	v_cmp_gt_f32_e32 vcc, 0, v19
	v_and_b32_e32 v32, 0x7fffffff, v20
	s_nop 0
	v_cndmask_b32_e32 v19, v33, v39, vcc
	v_and_b32_e32 v33, 0x7fffffff, v21
	v_pk_fma_f32 v[32:33], v[32:33], s[46:47], 1.0 op_sel_hi:[1,0,0]
	v_cmp_gt_f32_e32 vcc, 0, v20
	v_rcp_f32_e32 v32, v32
	v_rcp_f32_e32 v33, v33
	s_nop 0
	v_pk_fma_f32 v[34:35], v[32:33], s[48:49], v[34:35] op_sel_hi:[1,0,0]
	s_nop 0
	v_pk_fma_f32 v[34:35], v[32:33], v[34:35], s[52:53] op_sel_hi:[1,1,0]
	s_nop 0
	v_pk_fma_f32 v[34:35], v[32:33], v[34:35], s[54:55] op_sel_hi:[1,1,0]
	s_nop 0
	v_pk_fma_f32 v[34:35], v[32:33], v[34:35], s[56:57] op_sel_hi:[1,1,0]
	s_nop 0
	v_pk_mul_f32 v[32:33], v[32:33], v[34:35]
	v_pk_mul_f32 v[34:35], v[36:37], s[58:59] op_sel_hi:[1,0]
	s_nop 0
	v_exp_f32_e32 v34, v34
	v_exp_f32_e32 v35, v35
	s_nop 0
	v_pk_mul_f32 v[32:33], v[34:35], v[32:33]
	s_nop 0
	v_pk_mul_f32 v[34:35], v[20:21], v[32:33]
	v_pk_fma_f32 v[32:33], v[20:21], v[32:33], v[20:21] neg_lo:[1,0,0] neg_hi:[1,0,0]
	s_nop 0
	v_cndmask_b32_e32 v20, v32, v34, vcc
	v_cmp_gt_f32_e32 vcc, 0, v21
	s_nop 1
	v_cndmask_b32_e32 v21, v33, v35, vcc
.LBB0_359:
	s_and_b64 vcc, exec, s[2:3]
	s_cbranch_vccnz .LBB0_361
	v_pk_mul_f32 v[34:35], v[22:23], v[22:23]
	v_pk_mul_f32 v[32:33], v[24:25], v[24:25]
	v_pk_mov_b32 v[40:41], v[22:23], v[34:35] op_sel:[0,0]
	v_mov_b32_e32 v34, v23
	v_pk_add_f32 v[34:35], v[40:41], v[34:35]
	v_pk_mov_b32 v[40:41], v[24:25], v[32:33] op_sel:[0,0]
	v_mov_b32_e32 v32, v25
	v_pk_mul_f32 v[38:39], v[18:19], v[18:19]
	v_pk_add_f32 v[32:33], v[40:41], v[32:33]
	v_pk_mul_f32 v[36:37], v[20:21], v[20:21]
	v_pk_add_f32 v[32:33], v[34:35], v[32:33]
	v_pk_mov_b32 v[34:35], v[18:19], v[38:39] op_sel:[0,0]
	v_mov_b32_e32 v38, v19
	v_pk_add_f32 v[34:35], v[34:35], v[38:39]
	v_pk_mov_b32 v[38:39], v[20:21], v[36:37] op_sel:[0,0]
	v_mov_b32_e32 v36, v21
	v_pk_add_f32 v[36:37], v[38:39], v[36:37]
	s_nop 0
	v_pk_add_f32 v[34:35], v[34:35], v[36:37]
	s_nop 0
	v_pk_add_f32 v[32:33], v[34:35], v[32:33]
	s_nop 0
	v_pk_add_f32 v[28:29], v[28:29], v[32:33]

.LBB0_369:
	v_pk_mov_b32 v[12:13], v[0:1], v[0:1] op_sel:[1,1]
.LBB0_370:
	v_add_u32_e32 v10, 0xb0, v122
	v_mov_b64_e32 v[14:15], s[24:25]
	v_mov_b32_e32 v19, v18
	v_mad_i64_i32 v[14:15], s[12:13], v10, s49, v[14:15]
	v_cvt_pk_bf16_f32 v27, v16, v17
	v_pk_mov_b32 v[16:17], v[18:19], v[18:19] op_sel:[0,0]
	v_lshl_add_u64 v[14:15], v[0:1], 1, v[14:15]
	v_cvt_pk_bf16_f32 v24, v24, v25
	v_cvt_pk_bf16_f32 v25, v20, v21
	v_cvt_pk_bf16_f32 v26, v22, v23
	v_pk_mul_f32 v[8:9], v[8:9], v[16:17]
	v_pk_mul_f32 v[6:7], v[6:7], v[18:19]
	v_pk_mul_f32 v[4:5], v[4:5], v[16:17]
	s_and_b64 vcc, exec, s[2:3]
	v_pk_mul_f32 v[2:3], v[2:3], v[18:19]
	global_store_dwordx4 v[14:15], v[24:27], off
	s_cbranch_vccnz .LBB0_372
	v_and_b32_e32 v17, 0x7fffffff, v7
	v_and_b32_e32 v16, 0x7fffffff, v6
	v_pk_fma_f32 v[16:17], v[16:17], s[46:47], 1.0 op_sel_hi:[1,0,0]
	v_mov_b64_e32 v[18:19], s[50:51]
	v_rcp_f32_e32 v16, v16
	v_rcp_f32_e32 v17, v17
	v_pk_mul_f32 v[22:23], v[6:7], v[6:7]
	v_cmp_gt_f32_e32 vcc, 0, v6
	v_pk_mul_f32 v[22:23], v[22:23], s[58:59] op_sel_hi:[1,0]
	v_pk_fma_f32 v[20:21], v[16:17], s[48:49], v[18:19] op_sel_hi:[1,0,0]
	v_exp_f32_e32 v22, v22
	v_pk_fma_f32 v[20:21], v[16:17], v[20:21], s[52:53] op_sel_hi:[1,1,0]
	v_exp_f32_e32 v23, v23
	v_pk_fma_f32 v[20:21], v[16:17], v[20:21], s[54:55] op_sel_hi:[1,1,0]
	s_nop 0
	v_pk_fma_f32 v[20:21], v[16:17], v[20:21], s[56:57] op_sel_hi:[1,1,0]
	s_nop 0
	v_pk_mul_f32 v[16:17], v[16:17], v[20:21]
	v_pk_mul_f32 v[20:21], v[8:9], v[8:9]
	v_pk_mul_f32 v[16:17], v[22:23], v[16:17]
	v_pk_mul_f32 v[20:21], v[20:21], s[58:59] op_sel_hi:[1,0]
	v_pk_mul_f32 v[22:23], v[6:7], v[16:17]
	v_pk_fma_f32 v[16:17], v[6:7], v[16:17], v[6:7] neg_lo:[1,0,0] neg_hi:[1,0,0]
	v_exp_f32_e32 v20, v20
	v_cndmask_b32_e32 v6, v16, v22, vcc
	v_cmp_gt_f32_e32 vcc, 0, v7
	v_and_b32_e32 v16, 0x7fffffff, v8
	v_exp_f32_e32 v21, v21
	v_cndmask_b32_e32 v7, v17, v23, vcc
	v_and_b32_e32 v17, 0x7fffffff, v9
	v_pk_fma_f32 v[16:17], v[16:17], s[46:47], 1.0 op_sel_hi:[1,0,0]
	v_cmp_gt_f32_e32 vcc, 0, v8
	v_rcp_f32_e32 v16, v16
	v_rcp_f32_e32 v17, v17
	s_nop 0
	v_pk_fma_f32 v[22:23], v[16:17], s[48:49], v[18:19] op_sel_hi:[1,0,0]
	s_nop 0
	v_pk_fma_f32 v[22:23], v[16:17], v[22:23], s[52:53] op_sel_hi:[1,1,0]
	s_nop 0
	v_pk_fma_f32 v[22:23], v[16:17], v[22:23], s[54:55] op_sel_hi:[1,1,0]
	s_nop 0
	v_pk_fma_f32 v[22:23], v[16:17], v[22:23], s[56:57] op_sel_hi:[1,1,0]
	s_nop 0
	v_pk_mul_f32 v[16:17], v[16:17], v[22:23]
	v_pk_mul_f32 v[22:23], v[2:3], v[2:3]
	v_pk_mul_f32 v[16:17], v[20:21], v[16:17]
	v_pk_mul_f32 v[22:23], v[22:23], s[58:59] op_sel_hi:[1,0]
	v_pk_mul_f32 v[20:21], v[8:9], v[16:17]
	v_pk_fma_f32 v[16:17], v[8:9], v[16:17], v[8:9] neg_lo:[1,0,0] neg_hi:[1,0,0]
	v_exp_f32_e32 v22, v22
	v_cndmask_b32_e32 v8, v16, v20, vcc
	v_cmp_gt_f32_e32 vcc, 0, v9
	v_and_b32_e32 v16, 0x7fffffff, v2
	v_exp_f32_e32 v23, v23
	v_cndmask_b32_e32 v9, v17, v21, vcc
	v_and_b32_e32 v17, 0x7fffffff, v3
	v_pk_fma_f32 v[16:17], v[16:17], s[46:47], 1.0 op_sel_hi:[1,0,0]
	v_cmp_gt_f32_e32 vcc, 0, v2
	v_rcp_f32_e32 v16, v16
	v_rcp_f32_e32 v17, v17
	s_nop 0
	v_pk_fma_f32 v[20:21], v[16:17], s[48:49], v[18:19] op_sel_hi:[1,0,0]
	s_nop 0
	v_pk_fma_f32 v[20:21], v[16:17], v[20:21], s[52:53] op_sel_hi:[1,1,0]
	s_nop 0
	v_pk_fma_f32 v[20:21], v[16:17], v[20:21], s[54:55] op_sel_hi:[1,1,0]
	s_nop 0
	v_pk_fma_f32 v[20:21], v[16:17], v[20:21], s[56:57] op_sel_hi:[1,1,0]
	s_nop 0
	v_pk_mul_f32 v[16:17], v[16:17], v[20:21]
	v_pk_mul_f32 v[20:21], v[4:5], v[4:5]
	v_pk_mul_f32 v[16:17], v[22:23], v[16:17]
	s_nop 0
	v_pk_mul_f32 v[22:23], v[2:3], v[16:17]
	v_pk_fma_f32 v[16:17], v[2:3], v[16:17], v[2:3] neg_lo:[1,0,0] neg_hi:[1,0,0]
	s_nop 0
	v_cndmask_b32_e32 v2, v16, v22, vcc
	v_cmp_gt_f32_e32 vcc, 0, v3
	v_and_b32_e32 v16, 0x7fffffff, v4
	s_nop 0
	v_cndmask_b32_e32 v3, v17, v23, vcc
	v_and_b32_e32 v17, 0x7fffffff, v5
	v_pk_fma_f32 v[16:17], v[16:17], s[46:47], 1.0 op_sel_hi:[1,0,0]
	v_cmp_gt_f32_e32 vcc, 0, v4
	v_rcp_f32_e32 v16, v16
	v_rcp_f32_e32 v17, v17
	s_nop 0
	v_pk_fma_f32 v[18:19], v[16:17], s[48:49], v[18:19] op_sel_hi:[1,0,0]
	s_nop 0
	v_pk_fma_f32 v[18:19], v[16:17], v[18:19], s[52:53] op_sel_hi:[1,1,0]
	s_nop 0
	v_pk_fma_f32 v[18:19], v[16:17], v[18:19], s[54:55] op_sel_hi:[1,1,0]
	s_nop 0
	v_pk_fma_f32 v[18:19], v[16:17], v[18:19], s[56:57] op_sel_hi:[1,1,0]
	s_nop 0
	v_pk_mul_f32 v[16:17], v[16:17], v[18:19]
	v_pk_mul_f32 v[18:19], v[20:21], s[58:59] op_sel_hi:[1,0]
	s_nop 0
	v_exp_f32_e32 v18, v18
	v_exp_f32_e32 v19, v19
	s_nop 0
	v_pk_mul_f32 v[16:17], v[18:19], v[16:17]
	s_nop 0
	v_pk_mul_f32 v[18:19], v[4:5], v[16:17]
	v_pk_fma_f32 v[16:17], v[4:5], v[16:17], v[4:5] neg_lo:[1,0,0] neg_hi:[1,0,0]
	s_nop 0
	v_cndmask_b32_e32 v4, v16, v18, vcc
	v_cmp_gt_f32_e32 vcc, 0, v5
	s_nop 1
	v_cndmask_b32_e32 v5, v17, v19, vcc
.LBB0_372:
	s_and_b64 vcc, exec, s[2:3]
	s_cbranch_vccnz .LBB0_374
	v_pk_mul_f32 v[18:19], v[6:7], v[6:7]
	v_pk_mul_f32 v[16:17], v[8:9], v[8:9]
	v_pk_mov_b32 v[24:25], v[6:7], v[18:19] op_sel:[0,0]
	v_mov_b32_e32 v18, v7
	v_pk_add_f32 v[18:19], v[24:25], v[18:19]
	v_pk_mov_b32 v[24:25], v[8:9], v[16:17] op_sel:[0,0]
	v_mov_b32_e32 v16, v9
	v_pk_mul_f32 v[22:23], v[2:3], v[2:3]
	v_pk_add_f32 v[16:17], v[24:25], v[16:17]
	v_pk_mul_f32 v[20:21], v[4:5], v[4:5]
	v_pk_add_f32 v[16:17], v[18:19], v[16:17]
	v_pk_mov_b32 v[18:19], v[2:3], v[22:23] op_sel:[0,0]
	v_mov_b32_e32 v22, v3
	v_pk_add_f32 v[18:19], v[18:19], v[22:23]
	v_pk_mov_b32 v[22:23], v[4:5], v[20:21] op_sel:[0,0]
	v_mov_b32_e32 v20, v5
	v_pk_add_f32 v[20:21], v[22:23], v[20:21]
	s_nop 0
	v_pk_add_f32 v[18:19], v[18:19], v[20:21]
	s_nop 0
	v_pk_add_f32 v[16:17], v[18:19], v[16:17]
	s_nop 0
	v_pk_add_f32 v[12:13], v[12:13], v[16:17]

.LBB0_929:
	s_or_b64 exec, exec, s[88:89]
	v_mov_b64_e32 v[188:189], 0x200
	v_lshl_add_u32 v130, v134, 4, s79
	v_lshlrev_b32_e32 v0, 5, v0
	v_add_u32_e32 v186, s78, v0
	ds_read_b128 v[218:221], v130
	ds_read_b128 v[144:147], v186
	s_waitcnt lgkmcnt(0)
	ds_read_b128 v[130:133], v186 offset:16
	v_lshlrev_b32_e32 v187, 2, v134
	v_or_b32_e32 v0, s15, v187
	ds_read_b128 v[148:151], v186 offset:32
	ds_read_b128 v[138:141], v186 offset:48
	v_mov_b32_e32 v222, v221
	v_pk_mul_f32 v[198:199], v[110:111], v[222:223] op_sel_hi:[1,0]
	v_pk_mul_f32 v[180:181], v[114:115], v[220:221] op_sel_hi:[1,0]
	v_pk_mul_f32 v[168:169], v[98:99], v[222:223] op_sel_hi:[1,0]
	v_pk_mul_f32 v[170:171], v[102:103], v[220:221] op_sel_hi:[1,0]
	v_pk_mul_f32 v[172:173], v[126:127], v[218:219] op_sel_hi:[1,0]
	v_pk_mul_f32 v[126:127], v[118:119], v[218:219] op_sel_hi:[1,0]
	v_pk_mul_f32 v[174:175], v[122:123], v[218:219] op_sel:[0,1]
	v_pk_mul_f32 v[122:123], v[106:107], v[218:219] op_sel:[0,1]
	v_mov_b32_dpp v228, v198 row_shr:1 row_mask:0xf bank_mask:0xf bound_ctrl:1
	v_mov_b32_dpp v230, v180 row_shr:1 row_mask:0xf bank_mask:0xf bound_ctrl:1
	v_mov_b32_dpp v224, v168 row_shr:1 row_mask:0xf bank_mask:0xf bound_ctrl:1
	v_mov_b32_dpp v226, v170 row_shr:1 row_mask:0xf bank_mask:0xf bound_ctrl:1
	v_mov_b32_dpp v229, v199 row_shr:1 row_mask:0xf bank_mask:0xf bound_ctrl:1
	v_mov_b32_dpp v231, v181 row_shr:1 row_mask:0xf bank_mask:0xf bound_ctrl:1
	s_waitcnt lgkmcnt(1)
	v_pk_mov_b32 v[196:197], v[144:145], v[148:149] op_sel:[1,1]
	v_pk_mov_b32 v[194:195], v[146:147], v[150:151] op_sel:[0,0]
	v_mov_b32_e32 v145, v148
	v_mov_b32_e32 v150, v147
	v_mov_b32_dpp v225, v169 row_shr:1 row_mask:0xf bank_mask:0xf bound_ctrl:1
	v_mov_b32_dpp v227, v171 row_shr:1 row_mask:0xf bank_mask:0xf bound_ctrl:1
	s_waitcnt lgkmcnt(0)
	v_pk_mov_b32 v[182:183], v[130:131], v[138:139] op_sel:[0,0]
	v_pk_mov_b32 v[190:191], v[132:133], v[140:141] op_sel:[1,1]
	v_mov_b32_e32 v138, v131
	v_mov_b32_e32 v133, v140
	ds_read_b128 v[146:149], v186 offset:64
	ds_read_b128 v[134:137], v186 offset:80
	ds_read_b128 v[152:155], v186 offset:96
	ds_read_b128 v[140:143], v186 offset:112
	v_pk_mul_f32 v[206:207], v[112:113], v[222:223] op_sel_hi:[1,0]
	v_pk_mul_f32 v[192:193], v[116:117], v[220:221] op_sel_hi:[1,0]
	v_pk_mul_f32 v[130:131], v[100:101], v[222:223] op_sel_hi:[1,0]
	v_pk_mul_f32 v[176:177], v[104:105], v[220:221] op_sel_hi:[1,0]
	v_pk_mul_f32 v[178:179], v[128:129], v[218:219] op_sel_hi:[1,0]
	v_pk_mul_f32 v[128:129], v[120:121], v[218:219] op_sel_hi:[1,0]
	v_pk_mul_f32 v[184:185], v[124:125], v[218:219] op_sel:[0,1]
	v_pk_mul_f32 v[124:125], v[108:109], v[218:219] op_sel:[0,1]
	v_mov_b32_dpp v238, v206 row_shr:1 row_mask:0xf bank_mask:0xf bound_ctrl:1
	v_mov_b32_dpp v240, v192 row_shr:1 row_mask:0xf bank_mask:0xf bound_ctrl:1
	v_mov_b32_dpp v234, v130 row_shr:1 row_mask:0xf bank_mask:0xf bound_ctrl:1
	v_mov_b32_dpp v236, v176 row_shr:1 row_mask:0xf bank_mask:0xf bound_ctrl:1
	v_mov_b32_dpp v239, v207 row_shr:1 row_mask:0xf bank_mask:0xf bound_ctrl:1
	v_mov_b32_dpp v241, v193 row_shr:1 row_mask:0xf bank_mask:0xf bound_ctrl:1
	s_waitcnt lgkmcnt(3)
	s_waitcnt lgkmcnt(1)
	v_pk_mov_b32 v[214:215], v[146:147], v[152:153] op_sel:[1,1]
	v_pk_mov_b32 v[212:213], v[148:149], v[154:155] op_sel:[0,0]
	v_mov_b32_e32 v147, v152
	v_mov_b32_e32 v154, v149
	v_mov_b32_dpp v235, v131 row_shr:1 row_mask:0xf bank_mask:0xf bound_ctrl:1
	v_mov_b32_dpp v237, v177 row_shr:1 row_mask:0xf bank_mask:0xf bound_ctrl:1
	s_waitcnt lgkmcnt(0)
	v_pk_mov_b32 v[200:201], v[134:135], v[140:141] op_sel:[0,0]
	v_pk_mov_b32 v[204:205], v[136:137], v[142:143] op_sel:[1,1]
	v_mov_b32_e32 v140, v135
	v_mov_b32_e32 v137, v142
	ds_read_b128 v[114:117], v186 offset:128
	ds_read_b128 v[100:103], v186 offset:144
	ds_read_b128 v[118:121], v186 offset:160
	ds_read_b128 v[108:111], v186 offset:176
	v_pk_mul_f32 v[216:217], v[78:79], v[222:223] op_sel_hi:[1,0]
	v_pk_mul_f32 v[148:149], v[66:67], v[220:221] op_sel_hi:[1,0]
	v_pk_mul_f32 v[78:79], v[86:87], v[222:223] op_sel_hi:[1,0]
	v_pk_mul_f32 v[82:83], v[82:83], v[220:221] op_sel_hi:[1,0]
	v_pk_mul_f32 v[134:135], v[70:71], v[218:219] op_sel_hi:[1,0]
	v_pk_mul_f32 v[94:95], v[94:95], v[218:219] op_sel_hi:[1,0]
	v_pk_mul_f32 v[142:143], v[74:75], v[218:219] op_sel:[0,1]
	v_pk_mul_f32 v[74:75], v[90:91], v[218:219] op_sel:[0,1]
	v_mov_b32_dpp v242, v216 row_shr:1 row_mask:0xf bank_mask:0xf bound_ctrl:1
	v_mov_b32_dpp v244, v148 row_shr:1 row_mask:0xf bank_mask:0xf bound_ctrl:1
	v_mov_b32_dpp v66, v78 row_shr:1 row_mask:0xf bank_mask:0xf bound_ctrl:1
	v_mov_b32_dpp v70, v82 row_shr:1 row_mask:0xf bank_mask:0xf bound_ctrl:1
	v_mov_b32_dpp v243, v217 row_shr:1 row_mask:0xf bank_mask:0xf bound_ctrl:1
	v_mov_b32_dpp v245, v149 row_shr:1 row_mask:0xf bank_mask:0xf bound_ctrl:1
	s_waitcnt lgkmcnt(3)
	s_waitcnt lgkmcnt(1)
	v_pk_mov_b32 v[210:211], v[114:115], v[118:119] op_sel:[1,1]
	v_pk_mov_b32 v[208:209], v[116:117], v[120:121] op_sel:[0,0]
	v_mov_b32_e32 v115, v118
	v_mov_b32_e32 v120, v117
	v_mov_b32_dpp v67, v79 row_shr:1 row_mask:0xf bank_mask:0xf bound_ctrl:1
	v_mov_b32_dpp v71, v83 row_shr:1 row_mask:0xf bank_mask:0xf bound_ctrl:1
	s_waitcnt lgkmcnt(0)
	v_pk_mov_b32 v[152:153], v[100:101], v[108:109] op_sel:[0,0]
	v_pk_mov_b32 v[202:203], v[102:103], v[110:111] op_sel:[1,1]
	v_mov_b32_e32 v108, v101
	v_mov_b32_e32 v103, v110
	ds_read_b128 v[110:113], v186 offset:192
	ds_read_b128 v[98:101], v186 offset:208
	ds_read_b128 v[116:119], v186 offset:224
	ds_read_b128 v[104:107], v186 offset:240
	v_pk_mul_f32 v[90:91], v[72:73], v[218:219] op_sel_hi:[1,0]
	v_pk_mul_f32 v[86:87], v[96:97], v[218:219] op_sel_hi:[1,0]
	v_pk_mul_f32 v[96:97], v[76:77], v[218:219] op_sel:[0,1]
	v_pk_mul_f32 v[76:77], v[92:93], v[218:219] op_sel:[0,1]
	v_pk_mul_f32 v[218:219], v[80:81], v[222:223] op_sel_hi:[1,0]
	v_pk_mul_f32 v[92:93], v[68:69], v[220:221] op_sel_hi:[1,0]
	v_pk_mul_f32 v[80:81], v[88:89], v[222:223] op_sel_hi:[1,0]
	v_pk_mul_f32 v[84:85], v[84:85], v[220:221] op_sel_hi:[1,0]
	v_mov_b32_dpp v248, v218 row_shr:1 row_mask:0xf bank_mask:0xf bound_ctrl:1
	v_mov_b32_dpp v250, v92 row_shr:1 row_mask:0xf bank_mask:0xf bound_ctrl:1
	v_mov_b32_dpp v72, v80 row_shr:1 row_mask:0xf bank_mask:0xf bound_ctrl:1
	v_mov_b32_dpp v246, v84 row_shr:1 row_mask:0xf bank_mask:0xf bound_ctrl:1
	v_mov_b32_dpp v249, v219 row_shr:1 row_mask:0xf bank_mask:0xf bound_ctrl:1
	v_mov_b32_dpp v251, v93 row_shr:1 row_mask:0xf bank_mask:0xf bound_ctrl:1
	s_waitcnt lgkmcnt(3)
	s_waitcnt lgkmcnt(1)
	v_pk_mov_b32 v[222:223], v[110:111], v[116:117] op_sel:[1,1]
	v_pk_mov_b32 v[220:221], v[112:113], v[118:119] op_sel:[0,0]
	v_mov_b32_e32 v111, v116
	v_mov_b32_e32 v118, v113
	v_mov_b32_dpp v73, v81 row_shr:1 row_mask:0xf bank_mask:0xf bound_ctrl:1
	v_mov_b32_dpp v247, v85 row_shr:1 row_mask:0xf bank_mask:0xf bound_ctrl:1
	s_waitcnt lgkmcnt(0)
	v_pk_mov_b32 v[88:89], v[98:99], v[104:105] op_sel:[0,0]
	v_pk_mov_b32 v[112:113], v[100:101], v[106:107] op_sel:[1,1]
	v_mov_b32_e32 v104, v99
	v_mov_b32_e32 v101, v106
	v_lshlrev_b64 v[98:99], 1, v[232:233]
	s_and_saveexec_b64 s[4:5], vcc
	s_cbranch_execz .LBB0_931
	v_pk_fma_f32 v[68:69], v[110:111], v[248:249], v[118:119]
	v_pk_fma_f32 v[70:71], v[152:153], v[70:71], v[202:203]
	v_pk_fma_f32 v[68:69], v[90:91], v[222:223], v[68:69]
	s_nop 0
	v_pk_fma_f32 v[68:69], v[96:97], v[220:221], v[68:69]
	s_nop 0
	v_mul_f32_e32 v106, 0xbfb8aa3b, v68
	v_mul_f32_e32 v107, 0xbfb8aa3b, v69
	v_exp_f32_e32 v106, v106
	v_exp_f32_e32 v107, v107
	v_add_f32_e32 v106, 1.0, v106
	v_add_f32_e32 v107, 1.0, v107
	v_rcp_f32_e32 v106, v106
	v_rcp_f32_e32 v107, v107
	s_nop 0
	v_pk_mul_f32 v[68:69], v[68:69], v[106:107]
	v_pk_fma_f32 v[106:107], v[88:89], v[72:73], v[112:113]
	s_nop 0
	v_pk_fma_f32 v[106:107], v[86:87], v[104:105], v[106:107]
	s_nop 0
	v_pk_fma_f32 v[106:107], v[76:77], v[100:101], v[106:107]
	s_nop 0
	v_pk_mul_f32 v[68:69], v[106:107], v[68:69]
	v_pk_fma_f32 v[106:107], v[110:111], v[250:251], v[118:119]
	v_cvt_pk_bf16_f32 v69, v68, v69
	v_pk_fma_f32 v[106:107], v[222:223], v[248:249], v[106:107]
	s_nop 0
	v_pk_fma_f32 v[106:107], v[90:91], v[220:221], v[106:107]
	s_nop 0
	v_mul_f32_e32 v68, 0xbfb8aa3b, v106
	v_exp_f32_e32 v68, v68
	s_nop 0
	v_add_f32_e32 v68, 1.0, v68
	v_rcp_f32_e32 v116, v68
	v_mul_f32_e32 v68, 0xbfb8aa3b, v107
	v_exp_f32_e32 v68, v68
	s_nop 0
	v_add_f32_e32 v68, 1.0, v68
	v_rcp_f32_e32 v117, v68
	s_nop 0
	v_pk_mul_f32 v[106:107], v[106:107], v[116:117]
	v_pk_fma_f32 v[116:117], v[88:89], v[246:247], v[112:113]
	s_nop 0
	v_pk_fma_f32 v[72:73], v[104:105], v[72:73], v[116:117]
	s_nop 0
	v_pk_fma_f32 v[72:73], v[86:87], v[100:101], v[72:73]
	s_nop 0
	v_pk_mul_f32 v[72:73], v[72:73], v[106:107]
	v_pk_fma_f32 v[106:107], v[114:115], v[242:243], v[120:121]
	v_cvt_pk_bf16_f32 v73, v72, v73
	v_pk_fma_f32 v[106:107], v[134:135], v[210:211], v[106:107]
	s_nop 0
	v_pk_fma_f32 v[106:107], v[142:143], v[208:209], v[106:107]
	s_nop 0
	v_mul_f32_e32 v68, 0xbfb8aa3b, v106
	v_exp_f32_e32 v68, v68
	s_nop 0
	v_add_f32_e32 v68, 1.0, v68
	v_rcp_f32_e32 v116, v68
	v_mul_f32_e32 v68, 0xbfb8aa3b, v107
	v_exp_f32_e32 v68, v68
	s_nop 0
	v_add_f32_e32 v68, 1.0, v68
	v_rcp_f32_e32 v117, v68
	s_nop 0
	v_pk_mul_f32 v[106:107], v[106:107], v[116:117]
	v_pk_fma_f32 v[116:117], v[152:153], v[66:67], v[202:203]
	v_pk_fma_f32 v[66:67], v[108:109], v[66:67], v[70:71]
	v_pk_fma_f32 v[116:117], v[94:95], v[108:109], v[116:117]
	v_pk_fma_f32 v[66:67], v[94:95], v[102:103], v[66:67]
	v_pk_fma_f32 v[116:117], v[74:75], v[102:103], v[116:117]
	s_nop 0
	v_pk_mul_f32 v[106:107], v[116:117], v[106:107]
	s_nop 0
	v_cvt_pk_bf16_f32 v68, v106, v107
	v_pk_fma_f32 v[106:107], v[114:115], v[244:245], v[120:121]
	s_nop 0
	v_pk_fma_f32 v[106:107], v[210:211], v[242:243], v[106:107]
	s_nop 0
	v_pk_fma_f32 v[106:107], v[134:135], v[208:209], v[106:107]
	s_nop 0
	v_mul_f32_e32 v72, 0xbfb8aa3b, v106
	v_exp_f32_e32 v72, v72
	s_nop 0
	v_add_f32_e32 v72, 1.0, v72
	v_rcp_f32_e32 v116, v72
	v_mul_f32_e32 v72, 0xbfb8aa3b, v107
	v_exp_f32_e32 v72, v72
	s_nop 0
	v_add_f32_e32 v72, 1.0, v72
	v_rcp_f32_e32 v117, v72
	s_nop 0
	v_pk_mul_f32 v[106:107], v[106:107], v[116:117]
	s_nop 0
	v_pk_mul_f32 v[66:67], v[66:67], v[106:107]
	s_nop 0
	v_cvt_pk_bf16_f32 v72, v66, v67
	v_pk_fma_f32 v[66:67], v[146:147], v[238:239], v[154:155]
	s_nop 0
	v_pk_fma_f32 v[66:67], v[178:179], v[214:215], v[66:67]
	s_nop 0
	v_pk_fma_f32 v[66:67], v[184:185], v[212:213], v[66:67]
	s_nop 0
	v_mul_f32_e32 v70, 0xbfb8aa3b, v66
	v_mul_f32_e32 v71, 0xbfb8aa3b, v67
	v_exp_f32_e32 v70, v70
	v_exp_f32_e32 v71, v71
	v_add_f32_e32 v70, 1.0, v70
	v_add_f32_e32 v71, 1.0, v71
	v_rcp_f32_e32 v70, v70
	v_rcp_f32_e32 v71, v71
	s_nop 0
	v_pk_mul_f32 v[66:67], v[66:67], v[70:71]
	v_pk_fma_f32 v[70:71], v[200:201], v[234:235], v[204:205]
	s_nop 0
	v_pk_fma_f32 v[70:71], v[128:129], v[140:141], v[70:71]
	s_nop 0
	v_pk_fma_f32 v[70:71], v[124:125], v[136:137], v[70:71]
	s_nop 0
	v_pk_mul_f32 v[66:67], v[70:71], v[66:67]
	v_pk_fma_f32 v[70:71], v[146:147], v[240:241], v[154:155]
	v_cvt_pk_bf16_f32 v67, v66, v67
	v_pk_fma_f32 v[70:71], v[214:215], v[238:239], v[70:71]
	s_nop 0
	v_pk_fma_f32 v[70:71], v[178:179], v[212:213], v[70:71]
	s_nop 0
	v_mul_f32_e32 v66, 0xbfb8aa3b, v70
	v_exp_f32_e32 v66, v66
	s_nop 0
	v_add_f32_e32 v66, 1.0, v66
	v_rcp_f32_e32 v106, v66
	v_mul_f32_e32 v66, 0xbfb8aa3b, v71
	v_exp_f32_e32 v66, v66
	s_nop 0
	v_add_f32_e32 v66, 1.0, v66
	v_rcp_f32_e32 v107, v66
	s_nop 0
	v_pk_mul_f32 v[70:71], v[70:71], v[106:107]
	v_pk_fma_f32 v[106:107], v[200:201], v[236:237], v[204:205]
	s_nop 0
	v_pk_fma_f32 v[106:107], v[140:141], v[234:235], v[106:107]
	s_nop 0
	v_pk_fma_f32 v[106:107], v[128:129], v[136:137], v[106:107]
	s_nop 0
	v_pk_mul_f32 v[70:71], v[106:107], v[70:71]
	v_pk_fma_f32 v[106:107], v[144:145], v[228:229], v[150:151]
	v_cvt_pk_bf16_f32 v71, v70, v71
	v_pk_fma_f32 v[106:107], v[172:173], v[196:197], v[106:107]
	s_nop 0
	v_pk_fma_f32 v[106:107], v[194:195], v[174:175], v[106:107]
	s_nop 0
	v_mul_f32_e32 v66, 0xbfb8aa3b, v106
	v_exp_f32_e32 v66, v66
	s_nop 0
	v_add_f32_e32 v66, 1.0, v66
	v_rcp_f32_e32 v116, v66
	v_mul_f32_e32 v66, 0xbfb8aa3b, v107
	v_exp_f32_e32 v66, v66
	s_nop 0
	v_add_f32_e32 v66, 1.0, v66
	v_rcp_f32_e32 v117, v66
	s_nop 0
	v_pk_mul_f32 v[106:107], v[106:107], v[116:117]
	v_pk_fma_f32 v[116:117], v[182:183], v[224:225], v[190:191]
	s_nop 0
	v_pk_fma_f32 v[116:117], v[126:127], v[138:139], v[116:117]
	s_nop 0
	v_pk_fma_f32 v[116:117], v[122:123], v[132:133], v[116:117]
	s_nop 0
	v_pk_mul_f32 v[106:107], v[116:117], v[106:107]
	s_nop 0
	v_cvt_pk_bf16_f32 v66, v106, v107
	v_pk_fma_f32 v[106:107], v[144:145], v[230:231], v[150:151]
	s_nop 0
	v_pk_fma_f32 v[106:107], v[196:197], v[228:229], v[106:107]
	s_nop 0
	v_pk_fma_f32 v[106:107], v[194:195], v[172:173], v[106:107]
	s_nop 0
	v_mul_f32_e32 v70, 0xbfb8aa3b, v106
	v_exp_f32_e32 v70, v70
	s_nop 0
	v_add_f32_e32 v70, 1.0, v70
	v_rcp_f32_e32 v116, v70
	v_mul_f32_e32 v70, 0xbfb8aa3b, v107
	v_exp_f32_e32 v70, v70
	s_nop 0
	v_add_f32_e32 v70, 1.0, v70
	v_rcp_f32_e32 v117, v70
	s_nop 0
	v_pk_mul_f32 v[106:107], v[106:107], v[116:117]
	v_pk_fma_f32 v[116:117], v[182:183], v[226:227], v[190:191]
	s_nop 0
	v_pk_fma_f32 v[116:117], v[138:139], v[224:225], v[116:117]
	s_nop 0
	v_pk_fma_f32 v[116:117], v[126:127], v[132:133], v[116:117]
	s_nop 0
	v_pk_mul_f32 v[106:107], v[116:117], v[106:107]
	s_nop 0
	v_cvt_pk_bf16_f32 v70, v106, v107
	v_mov_b64_e32 v[106:107], s[24:25]
	v_mad_i64_i32 v[116:117], s[6:7], v0, s62, v[106:107]
	v_lshl_add_u64 v[116:117], v[116:117], 0, v[98:99]
	global_store_dwordx4 v[116:117], v[70:73], off
	s_nop 1
	v_or_b32_e32 v70, 1, v0
	v_mad_i64_i32 v[70:71], s[6:7], v70, s62, v[106:107]
	v_lshl_add_u64 v[70:71], v[70:71], 0, v[98:99]
	global_store_dwordx4 v[70:71], v[66:69], off
.LBB0_931:
	s_or_b64 exec, exec, s[4:5]
	s_nop 0
	v_pk_fma_f32 v[66:67], v[174:175], v[144:145], v[150:151]
	v_pk_fma_f32 v[70:71], v[172:173], v[144:145], v[150:151]
	v_pk_fma_f32 v[66:67], v[196:197], v[180:181], v[66:67]
	v_pk_fma_f32 v[70:71], v[174:175], v[196:197], v[70:71]
	v_pk_fma_f32 v[66:67], v[194:195], v[198:199], v[66:67]
	v_pk_fma_f32 v[70:71], v[180:181], v[194:195], v[70:71]
	v_mul_f32_e32 v68, 0xbfb8aa3b, v66
	v_mul_f32_e32 v69, 0xbfb8aa3b, v67
	v_exp_f32_e32 v68, v68
	v_exp_f32_e32 v69, v69
	v_mul_f32_e32 v72, 0xbfb8aa3b, v70
	v_mul_f32_e32 v73, 0xbfb8aa3b, v71
	v_exp_f32_e32 v72, v72
	v_exp_f32_e32 v73, v73
	v_add_f32_e32 v68, 1.0, v68
	v_add_f32_e32 v69, 1.0, v69
	v_rcp_f32_e32 v68, v68
	v_rcp_f32_e32 v69, v69
	v_add_f32_e32 v72, 1.0, v72
	v_add_f32_e32 v73, 1.0, v73
	v_rcp_f32_e32 v72, v72
	v_rcp_f32_e32 v73, v73
	v_pk_mul_f32 v[66:67], v[66:67], v[68:69]
	v_pk_fma_f32 v[68:69], v[126:127], v[182:183], v[190:191]
	v_pk_mul_f32 v[70:71], v[70:71], v[72:73]
	v_pk_fma_f32 v[68:69], v[122:123], v[138:139], v[68:69]
	s_nop 0
	v_pk_fma_f32 v[68:69], v[170:171], v[132:133], v[68:69]
	s_nop 0
	v_pk_mul_f32 v[68:69], v[68:69], v[70:71]
	v_pk_fma_f32 v[70:71], v[122:123], v[182:183], v[190:191]
	s_nop 0
	v_pk_fma_f32 v[70:71], v[170:171], v[138:139], v[70:71]
	s_nop 0
	v_pk_fma_f32 v[70:71], v[168:169], v[132:133], v[70:71]
	s_nop 0
	v_pk_mul_f32 v[70:71], v[70:71], v[66:67]
	v_cvt_pk_bf16_f32 v66, v68, v69
	v_pk_fma_f32 v[68:69], v[184:185], v[146:147], v[154:155]
	v_cvt_pk_bf16_f32 v106, v70, v71
	v_pk_fma_f32 v[68:69], v[192:193], v[214:215], v[68:69]
	s_nop 0
	v_pk_fma_f32 v[68:69], v[206:207], v[212:213], v[68:69]
	s_nop 0
	v_mul_f32_e32 v67, 0xbfb8aa3b, v68
	v_exp_f32_e32 v67, v67
	v_mul_f32_e32 v72, 0xbfb8aa3b, v69
	v_exp_f32_e32 v72, v72
	v_add_f32_e32 v67, 1.0, v67
	v_rcp_f32_e32 v70, v67
	v_add_f32_e32 v67, 1.0, v72
	v_pk_fma_f32 v[72:73], v[178:179], v[146:147], v[154:155]
	s_nop 0
	v_pk_fma_f32 v[72:73], v[184:185], v[214:215], v[72:73]
	s_nop 0
	v_pk_fma_f32 v[72:73], v[192:193], v[212:213], v[72:73]
	s_nop 0
	v_mul_f32_e32 v71, 0xbfb8aa3b, v72
	v_exp_f32_e32 v107, v71
	v_mul_f32_e32 v71, 0xbfb8aa3b, v73
	v_exp_f32_e32 v117, v71
	v_rcp_f32_e32 v71, v67
	v_add_f32_e32 v67, 1.0, v107
	v_rcp_f32_e32 v116, v67
	v_add_f32_e32 v67, 1.0, v117
	v_rcp_f32_e32 v117, v67
	v_pk_mul_f32 v[68:69], v[68:69], v[70:71]
	v_pk_fma_f32 v[70:71], v[128:129], v[200:201], v[204:205]
	v_pk_mul_f32 v[72:73], v[72:73], v[116:117]
	v_pk_fma_f32 v[70:71], v[124:125], v[140:141], v[70:71]
	s_nop 0
	v_pk_fma_f32 v[70:71], v[176:177], v[136:137], v[70:71]
	s_nop 0
	v_pk_mul_f32 v[70:71], v[70:71], v[72:73]
	v_pk_fma_f32 v[72:73], v[124:125], v[200:201], v[204:205]
	v_cvt_pk_bf16_f32 v67, v70, v71
	v_pk_fma_f32 v[70:71], v[142:143], v[114:115], v[120:121]
	v_pk_fma_f32 v[72:73], v[176:177], v[140:141], v[72:73]
	v_pk_fma_f32 v[70:71], v[148:149], v[210:211], v[70:71]
	v_pk_fma_f32 v[72:73], v[130:131], v[136:137], v[72:73]
	v_pk_fma_f32 v[70:71], v[216:217], v[208:209], v[70:71]
	v_pk_mul_f32 v[68:69], v[72:73], v[68:69]
	v_mul_f32_e32 v72, 0xbfb8aa3b, v70
	v_mul_f32_e32 v73, 0xbfb8aa3b, v71
	v_exp_f32_e32 v72, v72
	v_exp_f32_e32 v73, v73
	v_cvt_pk_bf16_f32 v107, v68, v69
	v_add_f32_e32 v68, 1.0, v72
	v_add_f32_e32 v69, 1.0, v73
	v_pk_fma_f32 v[72:73], v[134:135], v[114:115], v[120:121]
	v_rcp_f32_e32 v68, v68
	v_pk_fma_f32 v[72:73], v[142:143], v[210:211], v[72:73]
	v_rcp_f32_e32 v69, v69
	v_pk_fma_f32 v[72:73], v[148:149], v[208:209], v[72:73]
	v_pk_mul_f32 v[68:69], v[70:71], v[68:69]
	v_mul_f32_e32 v114, 0xbfb8aa3b, v72
	v_mul_f32_e32 v115, 0xbfb8aa3b, v73
	v_exp_f32_e32 v114, v114
	v_exp_f32_e32 v115, v115
	v_pk_fma_f32 v[70:71], v[94:95], v[152:153], v[202:203]
	v_add_f32_e32 v114, 1.0, v114
	v_add_f32_e32 v115, 1.0, v115
	v_rcp_f32_e32 v114, v114
	v_rcp_f32_e32 v115, v115
	v_pk_fma_f32 v[70:71], v[74:75], v[108:109], v[70:71]
	v_pk_mul_f32 v[72:73], v[72:73], v[114:115]
	v_pk_fma_f32 v[70:71], v[82:83], v[102:103], v[70:71]
	s_nop 0
	v_pk_mul_f32 v[70:71], v[70:71], v[72:73]
	v_pk_fma_f32 v[72:73], v[74:75], v[152:153], v[202:203]
	s_nop 0
	v_pk_fma_f32 v[72:73], v[82:83], v[108:109], v[72:73]
	s_nop 0
	v_pk_fma_f32 v[72:73], v[78:79], v[102:103], v[72:73]
	s_nop 0
	v_pk_mul_f32 v[72:73], v[72:73], v[68:69]
	v_cvt_pk_bf16_f32 v68, v70, v71
	v_pk_fma_f32 v[70:71], v[96:97], v[110:111], v[118:119]
	v_cvt_pk_bf16_f32 v108, v72, v73
	v_pk_fma_f32 v[70:71], v[92:93], v[222:223], v[70:71]
	s_nop 0
	v_pk_fma_f32 v[70:71], v[218:219], v[220:221], v[70:71]
	s_nop 0
	v_mul_f32_e32 v69, 0xbfb8aa3b, v70
	v_exp_f32_e32 v69, v69
	v_mul_f32_e32 v74, 0xbfb8aa3b, v71
	v_exp_f32_e32 v74, v74
	v_add_f32_e32 v69, 1.0, v69
	v_rcp_f32_e32 v72, v69
	v_add_f32_e32 v69, 1.0, v74
	v_pk_fma_f32 v[74:75], v[90:91], v[110:111], v[118:119]
	s_nop 0
	v_pk_fma_f32 v[74:75], v[96:97], v[222:223], v[74:75]
	s_nop 0
	v_pk_fma_f32 v[74:75], v[92:93], v[220:221], v[74:75]
	s_nop 0
	v_mul_f32_e32 v73, 0xbfb8aa3b, v74
	v_exp_f32_e32 v78, v73
	v_mul_f32_e32 v73, 0xbfb8aa3b, v75
	v_exp_f32_e32 v79, v73
	v_rcp_f32_e32 v73, v69
	v_add_f32_e32 v69, 1.0, v78
	v_rcp_f32_e32 v78, v69
	v_add_f32_e32 v69, 1.0, v79
	v_rcp_f32_e32 v79, v69
	v_pk_mul_f32 v[70:71], v[70:71], v[72:73]
	v_pk_fma_f32 v[72:73], v[86:87], v[88:89], v[112:113]
	v_pk_mul_f32 v[74:75], v[74:75], v[78:79]
	v_pk_fma_f32 v[72:73], v[76:77], v[104:105], v[72:73]
	s_nop 0
	v_pk_fma_f32 v[72:73], v[84:85], v[100:101], v[72:73]
	s_nop 0
	v_pk_mul_f32 v[72:73], v[72:73], v[74:75]
	v_pk_fma_f32 v[74:75], v[76:77], v[88:89], v[112:113]
	v_cvt_pk_bf16_f32 v69, v72, v73
	v_pk_fma_f32 v[74:75], v[84:85], v[104:105], v[74:75]
	v_or_b32_e32 v76, 3, v0
	v_pk_fma_f32 v[74:75], v[80:81], v[100:101], v[74:75]
	s_nop 0
	v_pk_mul_f32 v[70:71], v[74:75], v[70:71]
	v_mov_b64_e32 v[74:75], s[24:25]
	v_cvt_pk_bf16_f32 v109, v70, v71
	v_or_b32_e32 v70, 2, v0
	v_mad_i64_i32 v[70:71], s[4:5], v70, s62, v[74:75]
	v_lshl_add_u64 v[70:71], v[70:71], 0, v[98:99]
	global_store_dwordx4 v[70:71], v[66:69], off
	v_mad_i64_i32 v[74:75], s[4:5], v76, s62, v[74:75]
	s_nop 0
	v_lshl_add_u32 v66, v187, 2, s47
	ds_read_b128 v[136:139], v66
	ds_read_b128 v[70:73], v186
	ds_read_b128 v[66:69], v186 offset:16
	v_lshl_add_u64 v[74:75], v[74:75], 0, v[98:99]
	global_store_dwordx4 v[74:75], v[106:109], off
	ds_read_b128 v[78:81], v186 offset:32
	ds_read_b128 v[74:77], v186 offset:48
	s_waitcnt lgkmcnt(4)
	v_mov_b32_e32 v140, v139
	v_pk_mul_f32 v[110:111], v[54:55], v[138:139] op_sel_hi:[1,0]
	v_pk_mul_f32 v[104:105], v[38:39], v[138:139] op_sel_hi:[1,0]
	v_pk_mul_f32 v[114:115], v[42:43], v[140:141] op_sel_hi:[1,0]
	v_pk_mul_f32 v[112:113], v[34:35], v[140:141] op_sel_hi:[1,0]
	v_pk_mul_f32 v[106:107], v[62:63], v[136:137] op_sel_hi:[1,0]
	v_pk_mul_f32 v[108:109], v[58:59], v[136:137] op_sel:[0,1]
	v_pk_mul_f32 v[100:101], v[50:51], v[136:137] op_sel_hi:[1,0]
	v_pk_mul_f32 v[102:103], v[46:47], v[136:137] op_sel:[0,1]
	v_mov_b32_dpp v184, v110 row_shr:1 row_mask:0xf bank_mask:0xf bound_ctrl:1
	v_mov_b32_dpp v180, v104 row_shr:1 row_mask:0xf bank_mask:0xf bound_ctrl:1
	v_mov_b32_dpp v185, v111 row_shr:1 row_mask:0xf bank_mask:0xf bound_ctrl:1
	v_mov_b32_dpp v190, v114 row_shr:1 row_mask:0xf bank_mask:0xf bound_ctrl:1
	v_mov_b32_dpp v182, v112 row_shr:1 row_mask:0xf bank_mask:0xf bound_ctrl:1
	v_mov_b32_dpp v191, v115 row_shr:1 row_mask:0xf bank_mask:0xf bound_ctrl:1
	v_mov_b32_dpp v183, v113 row_shr:1 row_mask:0xf bank_mask:0xf bound_ctrl:1
	v_mov_b32_dpp v181, v105 row_shr:1 row_mask:0xf bank_mask:0xf bound_ctrl:1
	ds_read_b128 v[86:89], v186 offset:64
	ds_read_b128 v[82:85], v186 offset:80
	ds_read_b128 v[94:97], v186 offset:96
	ds_read_b128 v[90:93], v186 offset:112
	v_pk_mul_f32 v[126:127], v[56:57], v[138:139] op_sel_hi:[1,0]
	v_pk_mul_f32 v[120:121], v[40:41], v[138:139] op_sel_hi:[1,0]
	v_pk_mul_f32 v[130:131], v[44:45], v[140:141] op_sel_hi:[1,0]
	v_pk_mul_f32 v[128:129], v[36:37], v[140:141] op_sel_hi:[1,0]
	v_pk_mul_f32 v[122:123], v[64:65], v[136:137] op_sel_hi:[1,0]
	v_pk_mul_f32 v[124:125], v[60:61], v[136:137] op_sel:[0,1]
	v_pk_mul_f32 v[116:117], v[52:53], v[136:137] op_sel_hi:[1,0]
	v_pk_mul_f32 v[118:119], v[48:49], v[136:137] op_sel:[0,1]
	v_mov_b32_dpp v212, v126 row_shr:1 row_mask:0xf bank_mask:0xf bound_ctrl:1
	v_mov_b32_dpp v210, v120 row_shr:1 row_mask:0xf bank_mask:0xf bound_ctrl:1
	v_mov_b32_dpp v213, v127 row_shr:1 row_mask:0xf bank_mask:0xf bound_ctrl:1
	v_mov_b32_dpp v214, v130 row_shr:1 row_mask:0xf bank_mask:0xf bound_ctrl:1
	v_mov_b32_dpp v204, v128 row_shr:1 row_mask:0xf bank_mask:0xf bound_ctrl:1
	v_mov_b32_dpp v215, v131 row_shr:1 row_mask:0xf bank_mask:0xf bound_ctrl:1
	v_mov_b32_dpp v205, v129 row_shr:1 row_mask:0xf bank_mask:0xf bound_ctrl:1
	v_mov_b32_dpp v211, v121 row_shr:1 row_mask:0xf bank_mask:0xf bound_ctrl:1
	ds_read_b128 v[38:41], v186 offset:128
	ds_read_b128 v[34:37], v186 offset:144
	ds_read_b128 v[46:49], v186 offset:160
	ds_read_b128 v[42:45], v186 offset:176
	v_pk_mul_f32 v[132:133], v[10:11], v[136:137] op_sel_hi:[1,0]
	v_pk_mul_f32 v[10:11], v[26:27], v[136:137] op_sel_hi:[1,0]
	v_pk_mul_f32 v[26:27], v[6:7], v[138:139] op_sel_hi:[1,0]
	v_pk_mul_f32 v[6:7], v[22:23], v[138:139] op_sel_hi:[1,0]
	v_pk_mul_f32 v[22:23], v[2:3], v[140:141] op_sel_hi:[1,0]
	v_pk_mul_f32 v[18:19], v[18:19], v[140:141] op_sel_hi:[1,0]
	v_pk_mul_f32 v[134:135], v[14:15], v[136:137] op_sel:[0,1]
	v_pk_mul_f32 v[14:15], v[30:31], v[136:137] op_sel:[0,1]
	v_mov_b32_dpp v222, v26 row_shr:1 row_mask:0xf bank_mask:0xf bound_ctrl:1
	v_mov_b32_dpp v220, v6 row_shr:1 row_mask:0xf bank_mask:0xf bound_ctrl:1
	v_mov_b32_dpp v223, v27 row_shr:1 row_mask:0xf bank_mask:0xf bound_ctrl:1
	v_mov_b32_dpp v224, v22 row_shr:1 row_mask:0xf bank_mask:0xf bound_ctrl:1
	v_mov_b32_dpp v216, v18 row_shr:1 row_mask:0xf bank_mask:0xf bound_ctrl:1
	v_mov_b32_dpp v225, v23 row_shr:1 row_mask:0xf bank_mask:0xf bound_ctrl:1
	v_mov_b32_dpp v217, v19 row_shr:1 row_mask:0xf bank_mask:0xf bound_ctrl:1
	v_mov_b32_dpp v221, v7 row_shr:1 row_mask:0xf bank_mask:0xf bound_ctrl:1
	ds_read_b128 v[54:57], v186 offset:192
	ds_read_b128 v[50:53], v186 offset:208
	ds_read_b128 v[62:65], v186 offset:224
	ds_read_b128 v[58:61], v186 offset:240
	v_pk_mul_f32 v[150:151], v[8:9], v[138:139] op_sel_hi:[1,0]
	v_pk_mul_f32 v[8:9], v[24:25], v[138:139] op_sel_hi:[1,0]
	v_pk_mul_f32 v[178:179], v[4:5], v[140:141] op_sel_hi:[1,0]
	v_pk_mul_f32 v[172:173], v[20:21], v[140:141] op_sel_hi:[1,0]
	v_pk_mul_f32 v[148:149], v[12:13], v[136:137] op_sel_hi:[1,0]
	v_pk_mul_f32 v[146:147], v[16:17], v[136:137] op_sel:[0,1]
	v_pk_mul_f32 v[28:29], v[28:29], v[136:137] op_sel_hi:[1,0]
	v_pk_mul_f32 v[30:31], v[32:33], v[136:137] op_sel:[0,1]
	v_mov_b32_dpp v238, v150 row_shr:1 row_mask:0xf bank_mask:0xf bound_ctrl:1
	v_mov_b32_dpp v236, v8 row_shr:1 row_mask:0xf bank_mask:0xf bound_ctrl:1
	v_mov_b32_dpp v239, v151 row_shr:1 row_mask:0xf bank_mask:0xf bound_ctrl:1
	v_mov_b32_dpp v4, v178 row_shr:1 row_mask:0xf bank_mask:0xf bound_ctrl:1
	v_mov_b32_dpp v230, v172 row_shr:1 row_mask:0xf bank_mask:0xf bound_ctrl:1
	v_mov_b32_dpp v5, v179 row_shr:1 row_mask:0xf bank_mask:0xf bound_ctrl:1
	v_mov_b32_dpp v231, v173 row_shr:1 row_mask:0xf bank_mask:0xf bound_ctrl:1
	v_mov_b32_dpp v237, v9 row_shr:1 row_mask:0xf bank_mask:0xf bound_ctrl:1
	s_waitcnt lgkmcnt(14)
	s_waitcnt lgkmcnt(12)
	v_pk_mov_b32 v[142:143], v[68:69], v[76:77] op_sel:[1,1]
	v_pk_mov_b32 v[144:145], v[66:67], v[74:75] op_sel:[0,0]
	v_pk_mov_b32 v[12:13], v[66:67], v[74:75] op_sel:[1,1]
	v_pk_mov_b32 v[154:155], v[72:73], v[80:81] op_sel:[1,1]
	v_pk_mov_b32 v[168:169], v[70:71], v[78:79] op_sel:[0,0]
	v_pk_mov_b32 v[20:21], v[70:71], v[78:79] op_sel:[1,1]
	v_pk_mov_b32 v[16:17], v[68:69], v[76:77] op_sel:[0,0]
	v_pk_mov_b32 v[24:25], v[72:73], v[80:81] op_sel:[0,0]
	s_waitcnt lgkmcnt(10)
	s_waitcnt lgkmcnt(8)
	v_pk_mov_b32 v[200:201], v[84:85], v[92:93] op_sel:[1,1]
	v_pk_mov_b32 v[202:203], v[82:83], v[90:91] op_sel:[0,0]
	v_pk_mov_b32 v[32:33], v[82:83], v[90:91] op_sel:[1,1]
	v_pk_mov_b32 v[206:207], v[88:89], v[96:97] op_sel:[1,1]
	v_pk_mov_b32 v[208:209], v[86:87], v[94:95] op_sel:[0,0]
	v_pk_mov_b32 v[138:139], v[86:87], v[94:95] op_sel:[1,1]
	v_pk_mov_b32 v[136:137], v[84:85], v[92:93] op_sel:[0,0]
	v_pk_mov_b32 v[140:141], v[88:89], v[96:97] op_sel:[0,0]
	s_waitcnt lgkmcnt(6)
	s_waitcnt lgkmcnt(4)
	v_pk_mov_b32 v[2:3], v[36:37], v[44:45] op_sel:[1,1]
	v_pk_mov_b32 v[218:219], v[34:35], v[42:43] op_sel:[0,0]
	v_pk_mov_b32 v[152:153], v[34:35], v[42:43] op_sel:[1,1]
	v_pk_mov_b32 v[226:227], v[40:41], v[48:49] op_sel:[1,1]
	v_pk_mov_b32 v[228:229], v[38:39], v[46:47] op_sel:[0,0]
	v_pk_mov_b32 v[174:175], v[38:39], v[46:47] op_sel:[1,1]
	v_pk_mov_b32 v[170:171], v[36:37], v[44:45] op_sel:[0,0]
	v_pk_mov_b32 v[176:177], v[40:41], v[48:49] op_sel:[0,0]
	s_waitcnt lgkmcnt(2)
	s_waitcnt lgkmcnt(0)
	v_pk_mov_b32 v[232:233], v[52:53], v[60:61] op_sel:[1,1]
	v_pk_mov_b32 v[234:235], v[50:51], v[58:59] op_sel:[0,0]
	v_pk_mov_b32 v[192:193], v[50:51], v[58:59] op_sel:[1,1]
	v_pk_mov_b32 v[240:241], v[56:57], v[64:65] op_sel:[1,1]
	v_pk_mov_b32 v[242:243], v[54:55], v[62:63] op_sel:[0,0]
	v_pk_mov_b32 v[196:197], v[54:55], v[62:63] op_sel:[1,1]
	v_pk_mov_b32 v[194:195], v[52:53], v[60:61] op_sel:[0,0]
	v_pk_mov_b32 v[198:199], v[56:57], v[64:65] op_sel:[0,0]
	s_and_saveexec_b64 s[4:5], vcc
	s_xor_b64 s[4:5], exec, s[4:5]
	s_cbranch_execz .LBB0_915
	v_mov_b32_e32 v199, v64
	v_mov_b32_e32 v196, v55
	v_mov_b32_e32 v55, v62
	v_mov_b32_e32 v64, v57
	v_mov_b32_e32 v197, v63
	v_pk_fma_f32 v[2:3], v[54:55], v[4:5], v[64:65]
	v_mov_b32_e32 v198, v56
	v_pk_fma_f32 v[2:3], v[148:149], v[196:197], v[2:3]
	v_pk_fma_f32 v[16:17], v[54:55], v[238:239], v[64:65]
	v_pk_fma_f32 v[2:3], v[146:147], v[198:199], v[2:3]
	v_pk_fma_f32 v[4:5], v[196:197], v[4:5], v[16:17]
	v_mul_f32_e32 v12, 0xbfb8aa3b, v2
	v_mul_f32_e32 v13, 0xbfb8aa3b, v3
	v_exp_f32_e32 v12, v12
	v_exp_f32_e32 v13, v13
	v_pk_fma_f32 v[16:17], v[148:149], v[198:199], v[4:5]
	v_mov_b32_e32 v195, v60
	v_add_f32_e32 v12, 1.0, v12
	v_add_f32_e32 v13, 1.0, v13
	v_mul_f32_e32 v4, 0xbfb8aa3b, v16
	v_rcp_f32_e32 v12, v12
	v_rcp_f32_e32 v13, v13
	v_exp_f32_e32 v20, v4
	v_mul_f32_e32 v4, 0xbfb8aa3b, v17
	v_exp_f32_e32 v21, v4
	v_mov_b32_e32 v192, v51
	v_mov_b32_e32 v51, v58
	v_mov_b32_e32 v60, v53
	v_pk_mul_f32 v[2:3], v[2:3], v[12:13]
	v_mov_b32_e32 v193, v59
	v_pk_fma_f32 v[12:13], v[50:51], v[230:231], v[60:61]
	v_mov_b32_e32 v194, v52
	v_pk_fma_f32 v[4:5], v[28:29], v[192:193], v[12:13]
	v_add_f32_e32 v12, 1.0, v20
	v_add_f32_e32 v13, 1.0, v21
	v_rcp_f32_e32 v12, v12
	v_rcp_f32_e32 v13, v13
	v_pk_fma_f32 v[4:5], v[30:31], v[194:195], v[4:5]
	v_mov_b32_e32 v177, v48
	v_pk_mul_f32 v[2:3], v[4:5], v[2:3]
	v_mov_b32_e32 v174, v39
	v_mov_b32_e32 v39, v46
	v_mov_b32_e32 v48, v41
	v_cvt_pk_bf16_f32 v5, v2, v3
	v_pk_mul_f32 v[2:3], v[16:17], v[12:13]
	v_mov_b32_e32 v175, v47
	v_pk_fma_f32 v[16:17], v[38:39], v[224:225], v[48:49]
	v_mov_b32_e32 v176, v40
	v_pk_fma_f32 v[16:17], v[132:133], v[174:175], v[16:17]
	v_pk_fma_f32 v[12:13], v[50:51], v[236:237], v[60:61]
	v_pk_fma_f32 v[16:17], v[134:135], v[176:177], v[16:17]
	v_pk_fma_f32 v[12:13], v[192:193], v[230:231], v[12:13]
	v_mul_f32_e32 v4, 0xbfb8aa3b, v16
	v_exp_f32_e32 v4, v4
	v_mul_f32_e32 v20, 0xbfb8aa3b, v17
	v_exp_f32_e32 v21, v20
	v_pk_fma_f32 v[12:13], v[28:29], v[194:195], v[12:13]
	v_add_f32_e32 v4, 1.0, v4
	v_rcp_f32_e32 v20, v4
	v_add_f32_e32 v4, 1.0, v21
	v_rcp_f32_e32 v21, v4
	v_pk_mul_f32 v[2:3], v[12:13], v[2:3]
	v_mov_b32_e32 v171, v44
	v_cvt_pk_bf16_f32 v59, v2, v3
	v_pk_mul_f32 v[2:3], v[16:17], v[20:21]
	v_pk_fma_f32 v[16:17], v[38:39], v[222:223], v[48:49]
	v_mov_b32_e32 v152, v35
	v_pk_fma_f32 v[16:17], v[174:175], v[224:225], v[16:17]
	v_mov_b32_e32 v35, v42
	v_pk_fma_f32 v[16:17], v[132:133], v[176:177], v[16:17]
	v_mov_b32_e32 v44, v37
	v_mul_f32_e32 v4, 0xbfb8aa3b, v16
	v_exp_f32_e32 v4, v4
	v_mul_f32_e32 v20, 0xbfb8aa3b, v17
	v_exp_f32_e32 v21, v20
	v_mov_b32_e32 v153, v43
	v_add_f32_e32 v4, 1.0, v4
	v_rcp_f32_e32 v20, v4
	v_add_f32_e32 v4, 1.0, v21
	v_pk_fma_f32 v[12:13], v[34:35], v[216:217], v[44:45]
	v_rcp_f32_e32 v21, v4
	v_mov_b32_e32 v170, v36
	v_pk_fma_f32 v[12:13], v[10:11], v[152:153], v[12:13]
	v_mov_b32_e32 v141, v96
	v_pk_fma_f32 v[12:13], v[14:15], v[170:171], v[12:13]
	v_mov_b32_e32 v138, v87
	v_pk_mul_f32 v[2:3], v[12:13], v[2:3]
	v_mov_b32_e32 v87, v94
	v_mov_b32_e32 v96, v89
	v_cvt_pk_bf16_f32 v4, v2, v3
	v_pk_mul_f32 v[2:3], v[16:17], v[20:21]
	v_mov_b32_e32 v139, v95
	v_pk_fma_f32 v[16:17], v[86:87], v[214:215], v[96:97]
	v_mov_b32_e32 v140, v88
	v_pk_fma_f32 v[16:17], v[122:123], v[138:139], v[16:17]
	v_pk_fma_f32 v[12:13], v[34:35], v[220:221], v[44:45]
	v_pk_fma_f32 v[16:17], v[124:125], v[140:141], v[16:17]
	v_pk_fma_f32 v[12:13], v[152:153], v[216:217], v[12:13]
	v_mul_f32_e32 v20, 0xbfb8aa3b, v16
	v_mul_f32_e32 v21, 0xbfb8aa3b, v17
	v_exp_f32_e32 v20, v20
	v_exp_f32_e32 v21, v21
	v_pk_fma_f32 v[12:13], v[10:11], v[170:171], v[12:13]
	v_mov_b32_e32 v137, v92
	v_add_f32_e32 v20, 1.0, v20
	v_add_f32_e32 v21, 1.0, v21
	v_rcp_f32_e32 v20, v20
	v_rcp_f32_e32 v21, v21
	v_pk_mul_f32 v[2:3], v[12:13], v[2:3]
	v_mov_b32_e32 v32, v83
	v_cvt_pk_bf16_f32 v58, v2, v3
	v_pk_mul_f32 v[2:3], v[16:17], v[20:21]
	v_pk_fma_f32 v[16:17], v[86:87], v[212:213], v[96:97]
	v_mov_b32_e32 v83, v90
	v_pk_fma_f32 v[16:17], v[138:139], v[214:215], v[16:17]
	v_mov_b32_e32 v92, v85
	v_pk_fma_f32 v[16:17], v[122:123], v[140:141], v[16:17]
	v_mov_b32_e32 v33, v91
	v_mul_f32_e32 v20, 0xbfb8aa3b, v16
	v_mul_f32_e32 v21, 0xbfb8aa3b, v17
	v_exp_f32_e32 v20, v20
	v_exp_f32_e32 v21, v21
	v_pk_fma_f32 v[12:13], v[82:83], v[204:205], v[92:93]
	v_mov_b32_e32 v136, v84
	v_add_f32_e32 v20, 1.0, v20
	v_add_f32_e32 v21, 1.0, v21
	v_rcp_f32_e32 v20, v20
	v_rcp_f32_e32 v21, v21
	v_pk_fma_f32 v[12:13], v[116:117], v[32:33], v[12:13]
	v_mov_b32_e32 v25, v80
	v_pk_fma_f32 v[12:13], v[118:119], v[136:137], v[12:13]
	v_mov_b32_e32 v80, v73
	v_pk_mul_f32 v[2:3], v[12:13], v[2:3]
	v_pk_mul_f32 v[12:13], v[16:17], v[20:21]
	v_mov_b32_e32 v20, v71
	v_mov_b32_e32 v71, v78
	v_mov_b32_e32 v21, v79
	v_pk_fma_f32 v[36:37], v[70:71], v[190:191], v[80:81]
	v_mov_b32_e32 v24, v72
	v_pk_fma_f32 v[36:37], v[106:107], v[20:21], v[36:37]
	v_cvt_pk_bf16_f32 v3, v2, v3
	v_pk_fma_f32 v[36:37], v[108:109], v[24:25], v[36:37]
	v_pk_fma_f32 v[42:43], v[70:71], v[184:185], v[80:81]
	v_mul_f32_e32 v2, 0xbfb8aa3b, v36
	v_exp_f32_e32 v2, v2
	v_mul_f32_e32 v40, 0xbfb8aa3b, v37
	v_exp_f32_e32 v41, v40
	v_pk_fma_f32 v[42:43], v[20:21], v[190:191], v[42:43]
	v_add_f32_e32 v2, 1.0, v2
	v_rcp_f32_e32 v40, v2
	v_add_f32_e32 v2, 1.0, v41
	v_pk_fma_f32 v[42:43], v[106:107], v[24:25], v[42:43]
	v_rcp_f32_e32 v41, v2
	v_mul_f32_e32 v2, 0xbfb8aa3b, v42
	v_pk_fma_f32 v[16:17], v[82:83], v[210:211], v[92:93]
	v_exp_f32_e32 v2, v2
	v_mul_f32_e32 v46, 0xbfb8aa3b, v43
	v_pk_fma_f32 v[16:17], v[32:33], v[204:205], v[16:17]
	v_exp_f32_e32 v47, v46
	v_pk_fma_f32 v[16:17], v[116:117], v[136:137], v[16:17]
	v_add_f32_e32 v2, 1.0, v2
	v_pk_mul_f32 v[12:13], v[16:17], v[12:13]
	v_mov_b32_e32 v17, v76
	v_cvt_pk_bf16_f32 v57, v12, v13
	v_mov_b32_e32 v12, v67
	v_mov_b32_e32 v67, v74
	v_mov_b32_e32 v76, v69
	v_pk_mul_f32 v[36:37], v[36:37], v[40:41]
	v_mov_b32_e32 v13, v75
	v_pk_fma_f32 v[40:41], v[66:67], v[182:183], v[76:77]
	v_rcp_f32_e32 v46, v2
	v_add_f32_e32 v2, 1.0, v47
	v_mov_b32_e32 v16, v68
	v_pk_fma_f32 v[40:41], v[100:101], v[12:13], v[40:41]
	v_rcp_f32_e32 v47, v2
	v_pk_fma_f32 v[40:41], v[102:103], v[16:17], v[40:41]
	v_mov_b64_e32 v[242:243], v[54:55]
	v_pk_mul_f32 v[36:37], v[40:41], v[36:37]
	v_pk_fma_f32 v[40:41], v[66:67], v[180:181], v[76:77]
	v_cvt_pk_bf16_f32 v2, v36, v37
	v_pk_fma_f32 v[40:41], v[12:13], v[182:183], v[40:41]
	v_pk_mul_f32 v[36:37], v[42:43], v[46:47]
	v_pk_fma_f32 v[40:41], v[100:101], v[16:17], v[40:41]
	v_mov_b64_e32 v[240:241], v[64:65]
	v_pk_mul_f32 v[36:37], v[40:41], v[36:37]
	v_add_u32_e32 v40, 0x80, v0
	v_cvt_pk_bf16_f32 v56, v36, v37
	v_mov_b64_e32 v[36:37], s[24:25]
	v_mad_i64_i32 v[40:41], s[6:7], v40, s62, v[36:37]
	v_lshl_add_u64 v[40:41], v[40:41], 0, v[98:99]
	global_store_dwordx4 v[40:41], v[56:59], off
	v_add_u32_e32 v40, 0x81, v0
	v_mad_i64_i32 v[36:37], s[6:7], v40, s62, v[36:37]
	v_lshl_add_u64 v[36:37], v[36:37], 0, v[98:99]
	global_store_dwordx4 v[36:37], v[2:5], off
	v_mov_b64_e32 v[234:235], v[50:51]
	v_mov_b64_e32 v[232:233], v[60:61]
	v_mov_b64_e32 v[228:229], v[38:39]
	v_mov_b64_e32 v[226:227], v[48:49]
	v_mov_b64_e32 v[218:219], v[34:35]
	v_mov_b64_e32 v[2:3], v[44:45]
	v_mov_b64_e32 v[208:209], v[86:87]
	v_mov_b64_e32 v[206:207], v[96:97]
	v_mov_b64_e32 v[202:203], v[82:83]
	v_mov_b64_e32 v[200:201], v[92:93]
	v_mov_b64_e32 v[168:169], v[70:71]
	v_mov_b64_e32 v[154:155], v[80:81]
	v_mov_b64_e32 v[144:145], v[66:67]
	v_mov_b64_e32 v[142:143], v[76:77]
	s_branch .LBB0_915
